# attention phase: non-temporal hint on the read-once LDS-DMA loads (Q rows of a unit, Fourier item inputs) to keep K/V and partial Fourier output lines in L2
# baseline (speedup 1.0000x reference)
.LBB0_297:
	s_cmpk_gt_i32 s46, 0x4f
	v_readlane_b32 s4, v245, 14
	s_cselect_b64 s[2:3], -1, 0
	s_cmp_lt_u32 s46, s4
	s_cselect_b64 s[4:5], -1, 0
	s_and_b64 s[2:3], s[2:3], s[4:5]
	s_andn2_b64 vcc, exec, s[2:3]
	s_mov_b64 s[2:3], -1
	s_cbranch_vccz .LBB0_352
	s_cmpk_gt_i32 s46, 0x4f
	v_readlane_b32 s2, v245, 13
	s_cselect_b32 s2, s2, 0
	s_sub_i32 s2, s46, s2
	s_bfe_u32 s4, s2, 0x30001
	s_and_b32 s3, s2, 1
	s_xor_b32 s5, s4, 7
	s_or_b32 s4, s4, 8
	s_cmp_eq_u32 s3, 0
	s_cselect_b32 s3, s4, s5
	s_mov_b64 s[4:5], s[0:1]
	s_mov_b64 s[12:13], s[0:1]
	s_load_dwordx2 s[4:5], s[4:5], 0x80
	s_load_dwordx2 s[74:75], s[12:13], 0x80
	s_mov_b64 s[12:13], s[0:1]
	s_ashr_i32 s2, s2, 4
	s_load_dwordx2 s[78:79], s[12:13], 0x28
	s_sub_i32 s12, 8, s2
	v_cvt_f32_i32_e32 v0, s12
	v_mov_b32_e32 v19, v220
	v_readlane_b32 s13, v245, 17
	v_exp_f32_e64 v0, -v0
	s_sub_i32 s55, 7, s2
	s_lshl_b32 s76, s55, 6
	v_ashrrev_i32_e32 v2, 5, v19
	v_readfirstlane_b32 s12, v0
	v_ashrrev_i32_e32 v0, 3, v19
	v_add_u32_e32 v0, s13, v0
	v_mul_lo_u32 v3, v0, s88
	v_lshrrev_b32_e32 v0, 1, v0
	s_add_i32 s13, s76, 0x200
	v_xor_b32_e32 v0, v0, v19
	v_add_u32_e32 v3, s13, v3
	v_lshlrev_b32_e32 v0, 3, v0
	v_readlane_b32 s13, v245, 16
	v_and_or_b32 v0, v0, 56, v3
	v_lshlrev_b32_e32 v4, 3, v19
	v_lshl_add_u32 v3, v2, 3, s13
	v_readlane_b32 s13, v245, 18
	s_add_i32 s13, s13, s76
	v_and_b32_e32 v20, 24, v4
	v_or_b32_e32 v9, s13, v20
	v_readlane_b32 s13, v245, 19
	s_waitcnt lgkmcnt(0)
	s_add_u32 s4, s4, s13
	s_addc_u32 s5, s5, 0
	s_add_u32 s60, s4, 0x13200000
	s_addc_u32 s61, s5, 0
	s_mul_i32 s4, s3, 0xc0000
	s_add_u32 s80, s60, s4
	v_lshlrev_b32_e32 v0, 1, v0
	s_addc_u32 s81, s61, 0
	s_movk_i32 s4, 0xfc00
	v_lshl_add_u64 v[4:5], s[80:81], 0, v[0:1]
	s_mov_b32 s5, -1
	v_lshl_add_u64 v[6:7], v[4:5], 0, s[4:5]
	v_readlane_b32 s5, v245, 22
	s_mov_b32 s4, m0
	s_mov_b32 m0, s5
	s_nop 0
	global_load_lds_dwordx4 v[6:7], off nt
	s_mov_b32 m0, s4
	s_mov_b64 s[4:5], 0x2fc00
	v_bfe_u32 v8, v19, 2, 3
	v_lshl_add_u64 v[6:7], v[4:5], 0, s[4:5]
	v_readlane_b32 s5, v245, 20
	s_mov_b32 s4, m0
	s_mov_b32 m0, s5
	s_nop 0
	global_load_lds_dwordx4 v[6:7], off nt
	s_mov_b32 m0, s4
	s_mov_b64 s[4:5], 0x5fc00
	v_or_b32_e32 v3, v3, v8
	v_lshl_add_u64 v[6:7], v[4:5], 0, s[4:5]
	v_readlane_b32 s5, v245, 21
	s_mov_b32 s4, m0
	s_mov_b32 m0, s5
	s_nop 0
	global_load_lds_dwordx4 v[6:7], off nt
	s_mov_b32 m0, s4
	s_mov_b64 s[4:5], 0x8fc00
	v_mul_lo_u32 v3, v3, s88
	v_lshl_add_u64 v[6:7], v[4:5], 0, s[4:5]
	v_readlane_b32 s5, v245, 23
	s_mov_b32 s4, m0
	s_mov_b32 m0, s5
	s_nop 0
	global_load_lds_dwordx4 v[6:7], off nt
	s_mov_b32 m0, s4
	v_add_lshl_u32 v170, v9, v3, 1
	s_mov_b32 s4, m0
	s_mov_b32 m0, s64
	s_nop 0
	global_load_lds_dwordx4 v[4:5], off
	s_mov_b32 m0, s4
	v_mov_b32_e32 v171, v1
	v_lshl_add_u64 v[4:5], s[80:81], 0, v[170:171]
	v_readlane_b32 s5, v245, 24
	s_mov_b32 s4, m0
	s_mov_b32 m0, s5
	s_nop 0
	global_load_lds_dwordx4 v[4:5], off
	s_mov_b32 m0, s4
	v_lshlrev_b32_e32 v4, 2, v19
	v_readlane_b32 s4, v245, 25
	v_and_b32_e32 v9, 4, v4
	v_bitop3_b32 v4, v4, v8, 4 bitop3:0x6c
	v_lshl_add_u32 v3, v19, 6, s4
	v_and_b32_e32 v3, 0xffffff80, v3
	v_add_u32_e32 v3, s63, v3
	v_lshl_add_u32 v4, v4, 4, v3
	s_ashr_i32 s101, s2, 31
	s_mov_b32 s100, s2
	s_lshl_b64 s[100:101], s[100:101], 2
	s_sub_u32 s100, s7, s100
	s_subb_u32 s101, s33, s101
	v_mov_b32_e32 v248, 0
	global_load_dword v249, v248, s[100:101] offset:28 sc1
	s_add_u32 s100, s80, 0x30000
	s_addc_u32 s101, s81, 0
	v_lshl_add_u64 v[250:251], s[100:101], 0, v[0:1]
	v_lshl_add_u64 v[252:253], s[100:101], 0, v[170:171]
	v_readlane_b32 s98, v245, 27
	s_mov_b32 s99, m0
	s_mov_b32 m0, s98
	s_nop 0
	global_load_lds_dwordx4 v[250:251], off
	v_readlane_b32 s98, v245, 28
	s_nop 0
	s_mov_b32 m0, s98
	s_nop 0
	global_load_lds_dwordx4 v[252:253], off
	s_add_u32 s100, s80, 0x60000
	s_addc_u32 s101, s81, 0
	v_lshl_add_u64 v[250:251], s[100:101], 0, v[0:1]
	v_lshl_add_u64 v[252:253], s[100:101], 0, v[170:171]
	v_readlane_b32 s98, v245, 29
	s_nop 0
	s_mov_b32 m0, s98
	s_nop 0
	global_load_lds_dwordx4 v[250:251], off
	v_readlane_b32 s98, v245, 30
	s_nop 0
	s_mov_b32 m0, s98
	s_nop 0
	global_load_lds_dwordx4 v[252:253], off
	s_mov_b32 m0, s99
	s_waitcnt vmcnt(5)

.Lpipe_nofetch:
	s_add_u32 s2, s78, s8
	s_addc_u32 s3, s79, s9
	v_ashrrev_i32_e32 v173, 31, v172
	v_lshl_add_u64 v[2:3], v[172:173], 2, s[2:3]
	v_mov_b32_e32 v0, v175
	global_load_dwordx4 v[94:97], v[2:3], off
	global_load_dwordx4 v[90:93], v[2:3], off offset:32
	global_load_dwordx4 v[86:89], v[2:3], off offset:64
	global_load_dwordx4 v[82:85], v[2:3], off offset:96
	global_load_dwordx4 v[14:17], v[2:3], off offset:128
	global_load_dwordx4 v[10:13], v[2:3], off offset:160
	global_load_dwordx4 v[6:9], v[2:3], off offset:192
	s_nop 0
	global_load_dwordx4 v[2:5], v[2:3], off offset:224
	v_mov_b32_e32 v147, 0
	s_cmpk_gt_i32 s46, 0x4f
	v_readlane_b32 s2, v245, 13
	s_cselect_b32 s2, s2, 0
	s_sub_i32 s2, s46, s2
	s_bfe_u32 s4, s2, 0x30001
	s_and_b32 s3, s2, 1
	s_xor_b32 s5, s4, 7
	s_or_b32 s4, s4, 8
	s_cmp_eq_u32 s3, 0
	s_cselect_b32 s3, s4, s5
	s_mov_b64 s[4:5], s[0:1]
	s_mov_b64 s[12:13], s[0:1]
	s_load_dwordx2 s[4:5], s[4:5], 0x80
	s_mov_b64 s[12:13], s[0:1]
	s_ashr_i32 s2, s2, 4
	s_sub_i32 s12, 8, s2
	v_cvt_f32_i32_e32 v146, s12
	v_mov_b32_e32 v156, v220
	v_readlane_b32 s13, v245, 17
	v_exp_f32_e64 v146, -v146
	s_sub_i32 s55, 7, s2
	s_lshl_b32 s55, s55, 6
	v_ashrrev_i32_e32 v148, 5, v156
	v_readfirstlane_b32 s12, v146
	v_ashrrev_i32_e32 v146, 3, v156
	v_add_u32_e32 v146, s13, v146
	v_mul_lo_u32 v149, v146, s88
	v_lshrrev_b32_e32 v146, 1, v146
	s_add_i32 s13, s55, 0x200
	v_xor_b32_e32 v146, v146, v156
	v_add_u32_e32 v149, s13, v149
	v_lshlrev_b32_e32 v146, 3, v146
	v_readlane_b32 s13, v245, 16
	v_and_or_b32 v146, v146, 56, v149
	v_lshlrev_b32_e32 v150, 3, v156
	v_lshl_add_u32 v149, v148, 3, s13
	v_readlane_b32 s13, v245, 18
	s_add_i32 s13, s13, s55
	v_and_b32_e32 v157, 24, v150
	v_or_b32_e32 v155, s13, v157
	v_readlane_b32 s13, v245, 19
	s_waitcnt lgkmcnt(0)
	s_add_u32 s4, s4, s13
	s_addc_u32 s5, s5, 0
	s_add_u32 s60, s4, 0x13200000
	s_addc_u32 s61, s5, 0
	s_mul_i32 s4, s3, 0xc0000
	s_add_u32 s80, s60, s4
	v_lshlrev_b32_e32 v146, 1, v146
	s_addc_u32 s81, s61, 0
	s_movk_i32 s4, 0xfc00
	v_lshl_add_u64 v[150:151], s[80:81], 0, v[146:147]
	s_mov_b32 s5, -1
	v_lshl_add_u64 v[152:153], v[150:151], 0, s[4:5]
	v_readlane_b32 s5, v245, 22
	s_mov_b32 s4, m0
	s_mov_b32 m0, s5
	s_nop 0
	global_load_lds_dwordx4 v[152:153], off nt
	s_mov_b32 m0, s4
	s_mov_b64 s[4:5], 0x2fc00
	v_bfe_u32 v154, v156, 2, 3
	v_lshl_add_u64 v[152:153], v[150:151], 0, s[4:5]
	v_readlane_b32 s5, v245, 20
	s_mov_b32 s4, m0
	s_mov_b32 m0, s5
	s_nop 0
	global_load_lds_dwordx4 v[152:153], off nt
	s_mov_b32 m0, s4
	s_mov_b64 s[4:5], 0x5fc00
	v_or_b32_e32 v149, v149, v154
	v_lshl_add_u64 v[152:153], v[150:151], 0, s[4:5]
	v_readlane_b32 s5, v245, 21
	s_mov_b32 s4, m0
	s_mov_b32 m0, s5
	s_nop 0
	global_load_lds_dwordx4 v[152:153], off nt
	s_mov_b32 m0, s4
	s_mov_b64 s[4:5], 0x8fc00
	v_mul_lo_u32 v149, v149, s88
	v_lshl_add_u64 v[152:153], v[150:151], 0, s[4:5]
	v_readlane_b32 s5, v245, 23
	s_mov_b32 s4, m0
	s_mov_b32 m0, s5
	s_nop 0
	global_load_lds_dwordx4 v[152:153], off nt
	s_mov_b32 m0, s4
	v_add_lshl_u32 v170, v155, v149, 1
	s_mov_b32 s4, m0
	s_mov_b32 m0, s64
	s_nop 0
	global_load_lds_dwordx4 v[150:151], off
	s_mov_b32 m0, s4
	v_mov_b32_e32 v171, v1
	v_lshl_add_u64 v[150:151], s[80:81], 0, v[170:171]
	v_readlane_b32 s5, v245, 24
	s_mov_b32 s4, m0
	s_mov_b32 m0, s5
	s_nop 0
	global_load_lds_dwordx4 v[150:151], off
	s_mov_b32 m0, s4
	v_lshlrev_b32_e32 v150, 2, v156
	v_readlane_b32 s4, v245, 25
	v_and_b32_e32 v155, 4, v150
	v_bitop3_b32 v150, v150, v154, 4 bitop3:0x6c
	v_lshl_add_u32 v149, v156, 6, s4
	v_and_b32_e32 v149, 0xffffff80, v149
	v_add_u32_e32 v149, s63, v149
	v_lshl_add_u32 v150, v150, 4, v149
	s_ashr_i32 s101, s2, 31
	s_mov_b32 s100, s2
	s_lshl_b64 s[100:101], s[100:101], 2
	s_sub_u32 s100, s7, s100
	s_subb_u32 s101, s33, s101
	v_mov_b32_e32 v248, 0
	global_load_dword v249, v248, s[100:101] offset:28 sc1
	s_add_u32 s100, s80, 0x30000
	s_addc_u32 s101, s81, 0
	v_lshl_add_u64 v[250:251], s[100:101], 0, v[146:147]
	v_lshl_add_u64 v[252:253], s[100:101], 0, v[170:171]
	v_readlane_b32 s98, v245, 27
	s_mov_b32 s99, m0
	s_mov_b32 m0, s98
	s_nop 0
	global_load_lds_dwordx4 v[250:251], off
	v_readlane_b32 s98, v245, 28
	s_nop 0
	s_mov_b32 m0, s98
	s_nop 0
	global_load_lds_dwordx4 v[252:253], off
	s_add_u32 s100, s80, 0x60000
	s_addc_u32 s101, s81, 0
	v_lshl_add_u64 v[250:251], s[100:101], 0, v[146:147]
	v_lshl_add_u64 v[252:253], s[100:101], 0, v[170:171]
	v_readlane_b32 s98, v245, 29
	s_nop 0
	s_mov_b32 m0, s98
	s_nop 0
	global_load_lds_dwordx4 v[250:251], off
	v_readlane_b32 s98, v245, 30
	s_nop 0
	s_mov_b32 m0, s98
	s_nop 0
	global_load_lds_dwordx4 v[252:253], off
	s_mov_b32 m0, s99
	s_mov_b32 s4, s2
	s_mov_b32 s5, s3
	s_ashr_i32 s77, s76, 31
	v_permlane32_swap_b32_e32 v175, v0
	s_nop 0
	v_add_f32_e32 v0, v175, v0
	v_div_scale_f32 v98, s[2:3], v0, v0, 1.0
	v_rcp_f32_e32 v99, v98
	s_nop 0
	v_fma_f32 v100, -v98, v99, 1.0
	v_fmac_f32_e32 v99, v100, v99
	v_div_scale_f32 v100, vcc, 1.0, v0, 1.0
	v_mul_f32_e32 v101, v100, v99
	v_fma_f32 v102, -v98, v101, v100
	v_fmac_f32_e32 v101, v102, v99
	v_fma_f32 v98, -v98, v101, v100
	v_div_fmas_f32 v98, v98, v99, v101
	v_div_fixup_f32 v0, v98, v0, 1.0
	v_mov_b32_e32 v98, v174
	s_nop 1
	v_permlane32_swap_b32_e32 v174, v98
	s_nop 0
	v_add_f32_e32 v98, v174, v98
	v_div_scale_f32 v99, s[2:3], v98, v98, 1.0
	v_rcp_f32_e32 v100, v99
	s_mov_b32 s2, 0xf800000
	v_fma_f32 v101, -v99, v100, 1.0
	v_fmac_f32_e32 v100, v101, v100
	v_div_scale_f32 v101, vcc, 1.0, v98, 1.0
	v_mul_f32_e32 v102, v101, v100
	v_fma_f32 v103, -v99, v102, v101
	v_fmac_f32_e32 v102, v103, v100
	v_fma_f32 v99, -v99, v102, v101
	v_div_fmas_f32 v99, v99, v100, v102
	v_div_fixup_f32 v98, v99, v98, 1.0
	v_mul_f32_e32 v98, v183, v98
	v_mul_f32_e32 v66, v66, v98
	v_fma_f32 v50, v50, v0, -v66
	v_mul_f32_e32 v66, v67, v98
	v_fma_f32 v51, v51, v0, -v66
	v_mul_f32_e32 v66, v51, v51
	v_mul_f32_e32 v67, v68, v98
	v_fmac_f32_e32 v66, v50, v50
	v_fma_f32 v52, v52, v0, -v67
	v_mul_f32_e32 v67, v69, v98
	v_fmac_f32_e32 v66, v52, v52
	v_fma_f32 v53, v53, v0, -v67
	v_mul_f32_e32 v67, v70, v98
	v_fmac_f32_e32 v66, v53, v53
	v_fma_f32 v54, v54, v0, -v67
	v_mul_f32_e32 v67, v71, v98
	v_fmac_f32_e32 v66, v54, v54
	v_fma_f32 v55, v55, v0, -v67
	v_mul_f32_e32 v67, v72, v98
	v_fmac_f32_e32 v66, v55, v55
	v_fma_f32 v56, v56, v0, -v67
	v_mul_f32_e32 v67, v73, v98
	v_fmac_f32_e32 v66, v56, v56
	v_fma_f32 v57, v57, v0, -v67
	v_mul_f32_e32 v67, v74, v98
	v_fmac_f32_e32 v66, v57, v57
	v_fma_f32 v58, v58, v0, -v67
	v_mul_f32_e32 v67, v75, v98
	v_fmac_f32_e32 v66, v58, v58
	v_fma_f32 v59, v59, v0, -v67
	v_mul_f32_e32 v67, v76, v98
	v_fmac_f32_e32 v66, v59, v59
	v_fma_f32 v60, v60, v0, -v67
	v_mul_f32_e32 v67, v77, v98
	v_fmac_f32_e32 v66, v60, v60
	v_fma_f32 v61, v61, v0, -v67
	v_mul_f32_e32 v67, v78, v98
	v_fmac_f32_e32 v66, v61, v61
	v_fma_f32 v62, v62, v0, -v67
	v_mul_f32_e32 v67, v79, v98
	v_fmac_f32_e32 v66, v62, v62
	v_fma_f32 v63, v63, v0, -v67
	v_mul_f32_e32 v67, v80, v98
	v_fmac_f32_e32 v66, v63, v63
	v_fma_f32 v64, v64, v0, -v67
	v_mul_f32_e32 v67, v81, v98
	v_fmac_f32_e32 v66, v64, v64
	v_fma_f32 v65, v65, v0, -v67
	v_mul_f32_e32 v34, v34, v98
	v_fmac_f32_e32 v66, v65, v65
	v_fma_f32 v34, v18, v0, -v34
	v_mul_f32_e32 v18, v35, v98
	v_fmac_f32_e32 v66, v34, v34
	v_fma_f32 v35, v19, v0, -v18
	v_mul_f32_e32 v18, v36, v98
	v_fmac_f32_e32 v66, v35, v35
	v_fma_f32 v36, v20, v0, -v18
	v_mul_f32_e32 v18, v37, v98
	v_fmac_f32_e32 v66, v36, v36
	v_fma_f32 v37, v21, v0, -v18
	v_mul_f32_e32 v18, v38, v98
	v_fmac_f32_e32 v66, v37, v37
	v_fma_f32 v38, v22, v0, -v18
	v_mul_f32_e32 v18, v39, v98
	v_fmac_f32_e32 v66, v38, v38
	v_fma_f32 v39, v23, v0, -v18
	v_mul_f32_e32 v18, v40, v98
	v_fmac_f32_e32 v66, v39, v39
	v_fma_f32 v24, v24, v0, -v18
	v_mul_f32_e32 v18, v41, v98
	v_fmac_f32_e32 v66, v24, v24
	v_fma_f32 v25, v25, v0, -v18
	v_mul_f32_e32 v18, v42, v98
	v_fmac_f32_e32 v66, v25, v25
	v_fma_f32 v26, v26, v0, -v18
	v_mul_f32_e32 v18, v43, v98
	v_fmac_f32_e32 v66, v26, v26
	v_fma_f32 v27, v27, v0, -v18
	v_mul_f32_e32 v18, v44, v98
	v_fmac_f32_e32 v66, v27, v27
	v_fma_f32 v28, v28, v0, -v18
	v_mul_f32_e32 v18, v45, v98
	v_fmac_f32_e32 v66, v28, v28
	v_fma_f32 v29, v29, v0, -v18
	v_mul_f32_e32 v18, v46, v98
	v_fmac_f32_e32 v66, v29, v29
	v_fma_f32 v30, v30, v0, -v18
	v_mul_f32_e32 v18, v47, v98
	v_fmac_f32_e32 v66, v30, v30
	v_fma_f32 v31, v31, v0, -v18
	v_mul_f32_e32 v18, v48, v98
	v_fmac_f32_e32 v66, v31, v31
	v_fma_f32 v32, v32, v0, -v18
	v_mul_f32_e32 v18, v49, v98
	v_fmac_f32_e32 v66, v32, v32
	v_fma_f32 v33, v33, v0, -v18
	v_fmac_f32_e32 v66, v33, v33
	v_mov_b32_e32 v0, v66
	s_nop 1
	v_permlane32_swap_b32_e32 v66, v0
	s_nop 0
	v_add_f32_e32 v0, v66, v0
	v_fmamk_f32 v0, v0, 0x3c800000, v233
	v_cmp_gt_f32_e32 vcc, s2, v0
	v_mul_f32_e32 v18, 0x4f800000, v0
	s_nop 0
	v_cndmask_b32_e32 v0, v0, v18, vcc
	v_sqrt_f32_e32 v18, v0
	s_nop 0
	v_add_u32_e32 v19, -1, v18
	v_fma_f32 v20, -v19, v18, v0
	v_cmp_ge_f32_e64 s[2:3], 0, v20
	v_add_u32_e32 v20, 1, v18
	s_nop 0
	v_cndmask_b32_e64 v19, v18, v19, s[2:3]
	v_fma_f32 v18, -v20, v18, v0
	v_cmp_lt_f32_e64 s[2:3], 0, v18
	s_nop 1
	v_cndmask_b32_e64 v18, v19, v20, s[2:3]
	v_mul_f32_e32 v19, 0x37800000, v18
	v_cndmask_b32_e32 v18, v18, v19, vcc
	v_cmp_class_f32_e32 vcc, v0, v232
	s_nop 1
	v_cndmask_b32_e32 v0, v18, v0, vcc
	v_div_scale_f32 v18, s[2:3], v0, v0, v177
	v_rcp_f32_e32 v19, v18
	v_readlane_b32 s2, v244, 1
	s_add_i32 s2, s2, s68
	v_fma_f32 v20, -v18, v19, 1.0
	v_fmac_f32_e32 v19, v20, v19
	v_div_scale_f32 v20, vcc, v177, v0, v177
	v_mul_f32_e32 v21, v20, v19
	v_fma_f32 v22, -v18, v21, v20
	v_fmac_f32_e32 v21, v22, v19
	v_fma_f32 v18, -v18, v21, v20
	v_div_fmas_f32 v18, v18, v19, v21
	v_div_fixup_f32 v40, v18, v0, v177
	v_or_b32_e32 v0, s2, v185
	v_lshlrev_b64 v[18:19], 11, v[0:1]
	v_lshl_add_u64 v[18:19], s[74:75], 0, v[18:19]
	v_lshl_add_u64 v[18:19], s[76:77], 1, v[18:19]
	v_mul_f32_e32 v0, v50, v40
	v_mul_f32_e32 v20, v51, v40
	v_lshl_add_u64 v[18:19], v[172:173], 1, v[18:19]
	s_mov_b64 s[2:3], 0xb200000
	s_waitcnt vmcnt(18)
	v_mul_f32_e32 v0, v94, v0
	v_mul_f32_e32 v20, v95, v20
	v_lshl_add_u64 v[22:23], v[18:19], 0, s[2:3]
	s_mov_b32 s2, 0xb200000
	v_cvt_pk_bf16_f32 v20, v0, v20
	v_mul_f32_e32 v0, v52, v40
	v_mul_f32_e32 v21, v53, v40
	v_add_co_u32_e32 v18, vcc, s2, v18
	v_mul_f32_e32 v0, v96, v0
	v_mul_f32_e32 v21, v97, v21
	v_addc_co_u32_e32 v19, vcc, 0, v19, vcc
	v_cvt_pk_bf16_f32 v21, v0, v21
	global_store_dwordx2 v[18:19], v[20:21], off
	v_mul_f32_e32 v0, v54, v40
	v_mul_f32_e32 v18, v55, v40
	s_waitcnt vmcnt(18)
	v_mul_f32_e32 v0, v90, v0
	v_mul_f32_e32 v18, v91, v18
	v_cvt_pk_bf16_f32 v18, v0, v18
	v_mul_f32_e32 v0, v56, v40
	v_mul_f32_e32 v19, v57, v40
	v_mul_f32_e32 v0, v92, v0
	v_mul_f32_e32 v19, v93, v19
	v_cvt_pk_bf16_f32 v19, v0, v19
	global_store_dwordx2 v[22:23], v[18:19], off offset:16
	v_mul_f32_e32 v0, v58, v40
	v_mul_f32_e32 v18, v59, v40
	s_waitcnt vmcnt(18)
	v_mul_f32_e32 v0, v86, v0
	v_mul_f32_e32 v18, v87, v18
	v_cvt_pk_bf16_f32 v18, v0, v18
	v_mul_f32_e32 v0, v60, v40
	v_mul_f32_e32 v19, v61, v40
	v_mul_f32_e32 v0, v88, v0
	v_mul_f32_e32 v19, v89, v19
	v_cvt_pk_bf16_f32 v19, v0, v19
	global_store_dwordx2 v[22:23], v[18:19], off offset:32
	v_mul_f32_e32 v0, v62, v40
	v_mul_f32_e32 v18, v63, v40
	s_waitcnt vmcnt(18)
	v_mul_f32_e32 v0, v82, v0
	v_mul_f32_e32 v18, v83, v18
	v_cvt_pk_bf16_f32 v18, v0, v18
	v_mul_f32_e32 v0, v64, v40
	v_mul_f32_e32 v19, v65, v40
	v_mul_f32_e32 v0, v84, v0
	v_mul_f32_e32 v19, v85, v19
	v_cvt_pk_bf16_f32 v19, v0, v19
	v_mul_f32_e32 v0, v34, v40
	s_waitcnt vmcnt(17)
	v_mul_f32_e32 v0, v14, v0
	v_mul_f32_e32 v14, v35, v40
	v_mul_f32_e32 v14, v15, v14
	global_store_dwordx2 v[22:23], v[18:19], off offset:48
	v_cvt_pk_bf16_f32 v14, v0, v14
	v_mul_f32_e32 v0, v36, v40
	v_mul_f32_e32 v15, v37, v40
	v_mul_f32_e32 v0, v16, v0
	v_mul_f32_e32 v15, v17, v15
	v_cvt_pk_bf16_f32 v15, v0, v15
	v_mul_f32_e32 v0, v38, v40
	s_waitcnt vmcnt(17)
	v_mul_f32_e32 v0, v10, v0
	v_mul_f32_e32 v10, v39, v40
	v_mul_f32_e32 v10, v11, v10
	global_store_dwordx2 v[22:23], v[14:15], off offset:64
	v_cvt_pk_bf16_f32 v10, v0, v10
	v_mul_f32_e32 v0, v24, v40
	v_mul_f32_e32 v11, v25, v40
	v_mul_f32_e32 v0, v12, v0
	v_mul_f32_e32 v11, v13, v11
	v_cvt_pk_bf16_f32 v11, v0, v11
	v_mul_f32_e32 v0, v26, v40
	s_waitcnt vmcnt(17)
	v_mul_f32_e32 v0, v6, v0
	v_mul_f32_e32 v6, v27, v40
	v_mul_f32_e32 v6, v7, v6
	global_store_dwordx2 v[22:23], v[10:11], off offset:80
	v_cvt_pk_bf16_f32 v6, v0, v6
	v_mul_f32_e32 v0, v28, v40
	v_mul_f32_e32 v7, v29, v40
	v_mul_f32_e32 v0, v8, v0
	v_mul_f32_e32 v7, v9, v7
	v_cvt_pk_bf16_f32 v7, v0, v7
	v_mul_f32_e32 v0, v30, v40
	s_waitcnt vmcnt(17)
	v_mul_f32_e32 v0, v2, v0
	v_mul_f32_e32 v2, v31, v40
	v_mul_f32_e32 v2, v3, v2
	v_mul_f32_e32 v3, v33, v40
	global_store_dwordx2 v[22:23], v[6:7], off offset:96
	v_cvt_pk_bf16_f32 v2, v0, v2
	v_mul_f32_e32 v0, v32, v40
	v_mul_f32_e32 v3, v5, v3
	v_mul_f32_e32 v0, v4, v0
	v_cvt_pk_bf16_f32 v3, v0, v3
	global_store_dwordx2 v[22:23], v[2:3], off offset:112
	s_mov_b32 s2, s4
	s_mov_b32 s3, s5
	s_mov_b32 s76, s55
	v_mov_b32_e32 v0, v146
	v_mov_b32_e32 v2, v148
	v_mov_b32_e32 v3, v149
	v_mov_b32_e32 v4, v150
	v_mov_b32_e32 v8, v154
	v_mov_b32_e32 v9, v155
	v_mov_b32_e32 v19, v156
	v_mov_b32_e32 v20, v157
	s_waitcnt vmcnt(13)
	s_branch .Lpipe_part2

.LBB0_352:
	s_and_b64 vcc, exec, s[2:3]
	s_cbranch_vccz .LBB0_284
	v_readlane_b32 s2, v245, 31
	s_add_i32 s2, s2, s46
	s_cmpk_lt_u32 s46, 0x70
	v_readlane_b32 s3, v245, 32
	s_cselect_b32 s12, s2, s3
	s_cmpk_lt_u32 s12, 0x100
	s_cselect_b64 s[74:75], -1, 0
	s_lshl_b32 s56, s12, 3
	s_addk_i32 s56, 0xf800
	v_readlane_b32 s69, v245, 2
	s_and_b32 s57, s12, 7
	s_add_i32 s13, s56, s69
	s_lshl_b32 s60, s57, 3
	s_lshr_b32 s13, s13, 2
	s_lshr_b32 s61, s12, 5
	s_lshr_b32 s46, s12, 3
	s_add_i32 s55, s60, s69
	s_cmpk_gt_u32 s12, 0xff
	s_cselect_b32 s55, 64, s55
	s_cselect_b32 s68, s13, s61
	s_cselect_b32 s46, s69, s46
	s_cmp_lg_u32 s55, 64
	s_cselect_b64 s[12:13], -1, 0
	s_lshl_b32 s46, s46, 7
	s_lshl_b32 s69, s68, 9
	s_and_b32 s68, s46, 0x180
	s_mov_b64 s[2:3], s[0:1]
	s_or_b32 s76, s69, s68
	s_lshl_b32 s46, s55, 1
	s_load_dwordx2 s[4:5], s[2:3], 0x80
	s_ashr_i32 s77, s76, 31
	s_lshl_b64 s[78:79], s[46:47], 12
	s_or_b32 s46, s46, 1
	s_lshl_b64 s[76:77], s[76:77], 13
	s_lshl_b64 s[80:81], s[46:47], 12
	s_mov_b64 s[2:3], s[0:1]
	s_cmp_lg_u32 s55, 0
	v_mov_b32_e32 v130, v220
	s_cselect_b64 s[82:83], -1, 0
	s_load_dwordx2 s[2:3], s[2:3], 0x80
	s_and_b64 vcc, s[82:83], s[12:13]
	v_lshlrev_b32_e32 v0, 3, v130
	s_waitcnt lgkmcnt(0)
	s_add_u32 s76, s4, s76
	v_and_b32_e32 v22, 24, v0
	s_addc_u32 s77, s5, s77
	v_lshlrev_b32_e32 v13, 4, v130
	v_lshlrev_b32_e32 v0, 1, v22
	s_and_b64 s[4:5], s[12:13], exec
	v_and_b32_e32 v8, 0xffffffc0, v13
	v_lshl_add_u64 v[2:3], s[76:77], 0, v[0:1]
	s_mov_b64 s[76:77], 0x19200000
	s_cselect_b32 s13, s79, 0
	s_cselect_b32 s12, s78, 0x1000
	v_lshl_add_u64 v[4:5], v[2:3], 0, s[76:77]
	v_ashrrev_i32_e32 v9, 31, v8
	v_add_u32_e32 v14, 0x400, v8
	v_lshl_add_u64 v[10:11], s[12:13], 1, v[4:5]
	v_lshlrev_b64 v[6:7], 1, v[8:9]
	v_ashrrev_i32_e32 v15, 31, v14
	v_add_u32_e32 v18, 0x800, v8
	s_and_b64 s[4:5], vcc, exec
	v_lshl_add_u64 v[2:3], v[10:11], 0, v[6:7]
	s_mov_b32 m0, s65
	v_lshlrev_b64 v[14:15], 1, v[14:15]
	v_ashrrev_i32_e32 v19, 31, v18
	v_add_u32_e32 v8, 0xc00, v8
	s_cselect_b32 s5, s81, 0
	s_cselect_b32 s4, s80, 0x1000
	global_load_lds_dwordx4 v[2:3], off nt
	v_lshl_add_u64 v[16:17], v[10:11], 0, v[14:15]
	s_add_i32 m0, s65, 0x400
	v_lshlrev_b64 v[18:19], 1, v[18:19]
	v_ashrrev_i32_e32 v9, 31, v8
	global_load_lds_dwordx4 v[16:17], off nt
	v_lshl_add_u64 v[20:21], v[10:11], 0, v[18:19]
	s_add_i32 m0, s65, 0x800
	v_lshlrev_b64 v[8:9], 1, v[8:9]
	global_load_lds_dwordx4 v[20:21], off nt
	v_lshl_add_u64 v[10:11], v[10:11], 0, v[8:9]
	s_add_i32 m0, s65, 0xc00
	v_lshl_add_u64 v[4:5], s[4:5], 1, v[4:5]
	global_load_lds_dwordx4 v[10:11], off nt
	v_lshl_add_u64 v[6:7], v[4:5], 0, v[6:7]
	s_add_i32 m0, s65, 0x1000
	v_lshl_add_u64 v[14:15], v[4:5], 0, v[14:15]
	global_load_lds_dwordx4 v[6:7], off nt
	s_add_i32 m0, s65, 0x1400
	v_lshl_add_u64 v[18:19], v[4:5], 0, v[18:19]
	global_load_lds_dwordx4 v[14:15], off nt
	s_add_i32 m0, s65, 0x1800
	v_lshl_add_u64 v[4:5], v[4:5], 0, v[8:9]
	global_load_lds_dwordx4 v[18:19], off nt
	s_add_i32 m0, s65, 0x1c00
	v_readlane_b32 s4, v245, 34
	global_load_lds_dwordx4 v[4:5], off nt
	v_lshl_add_u64 v[2:3], v[2:3], 0, 64
	s_mov_b32 m0, s4
	v_readlane_b32 s4, v245, 35
	global_load_lds_dwordx4 v[2:3], off nt
	v_lshl_add_u64 v[2:3], v[16:17], 0, 64
	s_mov_b32 m0, s4
	v_readlane_b32 s4, v245, 36
	global_load_lds_dwordx4 v[2:3], off nt
	v_lshl_add_u64 v[2:3], v[20:21], 0, 64
	s_mov_b32 m0, s4
	v_readlane_b32 s4, v245, 37
	global_load_lds_dwordx4 v[2:3], off nt
	v_lshl_add_u64 v[2:3], v[10:11], 0, 64
	s_mov_b32 m0, s4
	v_readlane_b32 s4, v245, 38
	global_load_lds_dwordx4 v[2:3], off nt
	v_lshl_add_u64 v[2:3], v[6:7], 0, 64
	s_mov_b32 m0, s4
	v_readlane_b32 s4, v245, 39
	global_load_lds_dwordx4 v[2:3], off nt
	v_lshl_add_u64 v[2:3], v[14:15], 0, 64
	s_mov_b32 m0, s4
	v_readlane_b32 s4, v245, 40
	global_load_lds_dwordx4 v[2:3], off nt
	v_lshl_add_u64 v[2:3], v[18:19], 0, 64
	s_mov_b32 m0, s4
	v_readlane_b32 s4, v245, 41
	global_load_lds_dwordx4 v[2:3], off nt
	v_lshl_add_u64 v[2:3], v[4:5], 0, 64
	s_mov_b32 m0, s4
	v_readlane_b32 s4, v245, 33
	global_load_lds_dwordx4 v[2:3], off nt
	v_and_b32_e32 v2, 0xc0, v13
	v_ashrrev_i32_e32 v0, 5, v130
	v_or_b32_e32 v2, s4, v2
	v_lshlrev_b32_e32 v3, 1, v130
	v_and_b32_e32 v131, 31, v130
	v_lshrrev_b32_e32 v12, 1, v130
	v_lshl_add_u32 v2, v0, 9, v2
	v_and_b32_e32 v3, 32, v3
	v_or3_b32 v135, v2, v3, v22
	v_lshlrev_b32_e32 v133, 7, v131
	v_add_u32_e32 v2, 6, v0
	v_bitop3_b32 v10, v12, v0, 7 bitop3:0x6c
	v_bitop3_b32 v2, v2, v12, 7 bitop3:0x78
	s_add_i32 s4, 0, 0x20000
	v_add_u32_e32 v8, 0x1000, v135
	v_lshl_add_u32 v10, v10, 4, v133
	s_add_i32 s5, 0, 0x22000
	v_lshl_add_u32 v26, v2, 4, v133
	s_waitcnt vmcnt(8)
	ds_read_b64_tr_b16 v[2:3], v135
	ds_read_b64_tr_b16 v[4:5], v135 offset:256
	s_waitcnt lgkmcnt(0)
	ds_read_b64_tr_b16 v[6:7], v8
	ds_read_b64_tr_b16 v[8:9], v8 offset:256
	s_waitcnt lgkmcnt(0)
	v_add_u32_e32 v27, s4, v10
	v_add_u32_e32 v28, s5, v10
	ds_read_b128 v[18:21], v27
	ds_read_b128 v[22:25], v28
	s_waitcnt lgkmcnt(0)
	v_mfma_f32_32x32x16_bf16 v[98:113], v[2:5], v[18:21], 0
	v_cndmask_b32_e32 v6, 0, v6, vcc
	v_cndmask_b32_e32 v7, 0, v7, vcc
	v_cndmask_b32_e32 v8, 0, v8, vcc
	v_cndmask_b32_e32 v9, 0, v9, vcc
	v_xor_b32_e32 v14, 0x80008000, v6
	v_xor_b32_e32 v15, 0x80008000, v7
	v_xor_b32_e32 v16, 0x80008000, v8
	v_mfma_f32_32x32x16_bf16 v[114:129], v[2:5], v[22:25], 0
	v_xor_b32_e32 v17, 0x80008000, v9
	v_add_u32_e32 v10, 0x1000, v10
	v_add_u32_e32 v29, s4, v10
	v_add_u32_e32 v30, s5, v10
	v_add_u32_e32 v10, 2, v0
	v_bitop3_b32 v10, v10, v12, 7 bitop3:0x78
	v_lshl_add_u32 v10, v10, 4, v133
	v_mfma_f32_32x32x16_bf16 v[98:113], v[14:17], v[22:25], v[98:113]
	ds_read_b128 v[22:25], v30
	v_add_u32_e32 v148, s4, v10
	v_add_u32_e32 v152, s5, v10
	v_add_u32_e32 v10, 0x1000, v10
	v_add_u32_e32 v156, s4, v10
	v_add_u32_e32 v157, s5, v10
	v_add_u32_e32 v10, 4, v0
	v_mfma_f32_32x32x16_bf16 v[114:129], v[6:9], v[18:21], v[114:129]
	ds_read_b128 v[18:21], v29
	v_bitop3_b32 v10, v10, v12, 7 bitop3:0x78
	v_add_u32_e32 v134, s4, v26
	v_add_u32_e32 v162, s5, v26
	s_movk_i32 s12, 0x140
	v_bfe_u32 v132, v130, 1, 3
	s_waitcnt lgkmcnt(0)
	v_mfma_f32_32x32x16_bf16 v[82:97], v[2:5], v[22:25], 0
	v_mfma_f32_32x32x16_bf16 v[66:81], v[2:5], v[18:21], 0
	v_add_u32_e32 v4, 0x400, v135
	ds_read_b64_tr_b16 v[2:3], v4
	ds_read_b64_tr_b16 v[4:5], v4 offset:256
	s_waitcnt lgkmcnt(0)
	v_mfma_f32_32x32x16_bf16 v[82:97], v[6:9], v[18:21], v[82:97]
	v_add_u32_e32 v8, 0x1400, v135
	ds_read_b64_tr_b16 v[6:7], v8
	ds_read_b64_tr_b16 v[8:9], v8 offset:256
	s_waitcnt lgkmcnt(0)
	ds_read_b128 v[18:21], v148
	v_cndmask_b32_e32 v6, 0, v6, vcc
	v_cndmask_b32_e32 v7, 0, v7, vcc
	v_mfma_f32_32x32x16_bf16 v[66:81], v[14:17], v[22:25], v[66:81]
	ds_read_b128 v[22:25], v152
	v_cndmask_b32_e32 v8, 0, v8, vcc
	v_cndmask_b32_e32 v9, 0, v9, vcc
	v_xor_b32_e32 v14, 0x80008000, v6
	v_xor_b32_e32 v15, 0x80008000, v7
	v_xor_b32_e32 v16, 0x80008000, v8
	v_xor_b32_e32 v17, 0x80008000, v9
	s_waitcnt lgkmcnt(0)
	v_mfma_f32_32x32x16_bf16 v[98:113], v[2:5], v[18:21], v[98:113]
	v_mfma_f32_32x32x16_bf16 v[114:129], v[2:5], v[22:25], v[114:129]
	v_mfma_f32_32x32x16_bf16 v[98:113], v[14:17], v[22:25], v[98:113]
	ds_read_b128 v[22:25], v157
	v_mfma_f32_32x32x16_bf16 v[114:129], v[6:9], v[18:21], v[114:129]
	ds_read_b128 v[18:21], v156
	s_waitcnt lgkmcnt(0)
	v_mfma_f32_32x32x16_bf16 v[66:81], v[2:5], v[18:21], v[66:81]
	v_mfma_f32_32x32x16_bf16 v[82:97], v[2:5], v[22:25], v[82:97]
	v_add_u32_e32 v4, 0x800, v135
	ds_read_b64_tr_b16 v[2:3], v4
	ds_read_b64_tr_b16 v[4:5], v4 offset:256
	s_waitcnt lgkmcnt(0)
	v_mfma_f32_32x32x16_bf16 v[66:81], v[14:17], v[22:25], v[66:81]
	v_lshl_add_u32 v22, v10, 4, v133
	v_add_u32_e32 v158, s4, v22
	v_add_u32_e32 v159, s5, v22
	v_mfma_f32_32x32x16_bf16 v[82:97], v[6:9], v[18:21], v[82:97]
	v_add_u32_e32 v8, 0x1800, v135
	ds_read_b64_tr_b16 v[6:7], v8
	ds_read_b64_tr_b16 v[8:9], v8 offset:256
	s_waitcnt lgkmcnt(0)
	ds_read_b128 v[10:13], v158
	ds_read_b128 v[18:21], v159
	v_cndmask_b32_e32 v6, 0, v6, vcc
	s_waitcnt lgkmcnt(0)
	v_mfma_f32_32x32x16_bf16 v[98:113], v[2:5], v[10:13], v[98:113]
	v_cndmask_b32_e32 v7, 0, v7, vcc
	v_cndmask_b32_e32 v8, 0, v8, vcc
	v_cndmask_b32_e32 v9, 0, v9, vcc
	v_xor_b32_e32 v14, 0x80008000, v6
	v_xor_b32_e32 v15, 0x80008000, v7
	v_xor_b32_e32 v16, 0x80008000, v8
	v_xor_b32_e32 v17, 0x80008000, v9
	v_mfma_f32_32x32x16_bf16 v[114:129], v[2:5], v[18:21], v[114:129]
	s_nop 0
	v_mfma_f32_32x32x16_bf16 v[98:113], v[14:17], v[18:21], v[98:113]
	v_add_u32_e32 v18, 0x1000, v22
	v_add_u32_e32 v160, s4, v18
	v_add_u32_e32 v161, s5, v18
	ds_read_b128 v[18:21], v161
	v_mfma_f32_32x32x16_bf16 v[114:129], v[6:9], v[10:13], v[114:129]
	ds_read_b128 v[10:13], v160
	s_waitcnt lgkmcnt(0)
	v_mfma_f32_32x32x16_bf16 v[82:97], v[2:5], v[18:21], v[82:97]
	v_mfma_f32_32x32x16_bf16 v[66:81], v[2:5], v[10:13], v[66:81]
	v_add_u32_e32 v4, 0xc00, v135
	ds_read_b64_tr_b16 v[2:3], v4
	ds_read_b64_tr_b16 v[4:5], v4 offset:256
	s_waitcnt lgkmcnt(0)
	v_mfma_f32_32x32x16_bf16 v[82:97], v[6:9], v[10:13], v[82:97]
	v_add_u32_e32 v8, 0x1c00, v135
	ds_read_b64_tr_b16 v[6:7], v8
	ds_read_b64_tr_b16 v[8:9], v8 offset:256
	s_waitcnt lgkmcnt(0)
	s_nop 0
	v_cndmask_b32_e32 v6, 0, v6, vcc
	v_cndmask_b32_e32 v7, 0, v7, vcc
	v_mfma_f32_32x32x16_bf16 v[66:81], v[14:17], v[18:21], v[66:81]
	ds_read_b128 v[14:17], v134
	ds_read_b128 v[18:21], v162
	v_cndmask_b32_e32 v8, 0, v8, vcc
	v_cndmask_b32_e32 v9, 0, v9, vcc
	v_xor_b32_e32 v10, 0x80008000, v6
	v_xor_b32_e32 v11, 0x80008000, v7
	v_xor_b32_e32 v12, 0x80008000, v8
	s_waitcnt lgkmcnt(0)
	v_mfma_f32_32x32x16_bf16 v[98:113], v[2:5], v[14:17], v[98:113]
	v_xor_b32_e32 v13, 0x80008000, v9
	v_mfma_f32_32x32x16_bf16 v[114:129], v[2:5], v[18:21], v[114:129]
	s_nop 0
	v_mfma_f32_32x32x16_bf16 v[98:113], v[10:13], v[18:21], v[98:113]
	v_add_u32_e32 v18, 0x1000, v26
	v_add_u32_e32 v163, s4, v18
	v_add_u32_e32 v164, s5, v18
	ds_read_b128 v[18:21], v164
	v_mfma_f32_32x32x16_bf16 v[114:129], v[6:9], v[14:17], v[114:129]
	ds_read_b128 v[14:17], v163
	s_waitcnt vmcnt(0)
	s_waitcnt lgkmcnt(0)
	v_mfma_f32_32x32x16_bf16 v[66:81], v[2:5], v[14:17], v[66:81]
	v_mfma_f32_32x32x16_bf16 v[82:97], v[2:5], v[18:21], v[82:97]
	v_add_u32_e32 v2, 0x10000, v135
	v_add_u32_e32 v4, 0x11000, v135
	v_mfma_f32_32x32x16_bf16 v[66:81], v[10:13], v[18:21], v[66:81]
	ds_read_b64_tr_b16 v[18:19], v2
	ds_read_b64_tr_b16 v[20:21], v2 offset:256
	s_waitcnt lgkmcnt(0)
	ds_read_b64_tr_b16 v[2:3], v4
	ds_read_b64_tr_b16 v[4:5], v4 offset:256
	s_waitcnt lgkmcnt(0)
	v_mfma_f32_32x32x16_bf16 v[82:97], v[6:9], v[14:17], v[82:97]
	v_cndmask_b32_e32 v136, 0, v2, vcc
	v_cndmask_b32_e32 v137, 0, v3, vcc
	v_cndmask_b32_e32 v138, 0, v4, vcc
	v_cndmask_b32_e32 v139, 0, v5, vcc
	ds_read_b128 v[2:5], v27
	ds_read_b128 v[6:9], v28
	v_xor_b32_e32 v22, 0x80008000, v136
	v_xor_b32_e32 v23, 0x80008000, v137
	s_waitcnt lgkmcnt(0)
	v_mfma_f32_32x32x16_bf16 v[34:49], v[18:21], v[2:5], 0
	v_xor_b32_e32 v24, 0x80008000, v138
	v_xor_b32_e32 v25, 0x80008000, v139
	ds_read_b128 v[140:143], v29
	ds_read_b128 v[26:29], v30
	v_mfma_f32_32x32x16_bf16 v[50:65], v[18:21], v[6:9], 0
	v_mfma_f32_32x32x16_bf16 v[34:49], v[22:25], v[6:9], v[34:49]
	v_mfma_f32_32x32x16_bf16 v[50:65], v[136:139], v[2:5], v[50:65]
	s_waitcnt lgkmcnt(0)
	v_mfma_f32_32x32x16_bf16 v[2:17], v[18:21], v[140:143], 0
	v_mfma_f32_32x32x16_bf16 v[2:17], v[22:25], v[26:29], v[2:17]
	v_mfma_f32_32x32x16_bf16 v[18:33], v[18:21], v[26:29], 0
	v_mfma_f32_32x32x16_bf16 v[18:33], v[136:139], v[140:143], v[18:33]
	v_add_u32_e32 v138, 0x10400, v135
	v_add_u32_e32 v142, 0x11400, v135
	ds_read_b64_tr_b16 v[136:137], v138
	ds_read_b64_tr_b16 v[138:139], v138 offset:256
	s_waitcnt lgkmcnt(0)
	ds_read_b64_tr_b16 v[140:141], v142
	ds_read_b64_tr_b16 v[142:143], v142 offset:256
	s_waitcnt lgkmcnt(0)
	ds_read_b128 v[148:151], v148
	ds_read_b128 v[152:155], v152
	s_waitcnt lgkmcnt(0)
	v_mfma_f32_32x32x16_bf16 v[34:49], v[136:139], v[148:151], v[34:49]
	v_cndmask_b32_e32 v140, 0, v140, vcc
	v_cndmask_b32_e32 v141, 0, v141, vcc
	v_cndmask_b32_e32 v142, 0, v142, vcc
	v_cndmask_b32_e32 v143, 0, v143, vcc
	v_xor_b32_e32 v144, 0x80008000, v140
	v_xor_b32_e32 v145, 0x80008000, v141
	v_xor_b32_e32 v146, 0x80008000, v142
	v_mfma_f32_32x32x16_bf16 v[50:65], v[136:139], v[152:155], v[50:65]
	v_xor_b32_e32 v147, 0x80008000, v143
	s_nop 1
	v_mfma_f32_32x32x16_bf16 v[34:49], v[144:147], v[152:155], v[34:49]
	v_mfma_f32_32x32x16_bf16 v[50:65], v[140:143], v[148:151], v[50:65]
	ds_read_b128 v[148:151], v156
	ds_read_b128 v[152:155], v157
	s_waitcnt lgkmcnt(0)
	v_mfma_f32_32x32x16_bf16 v[18:33], v[136:139], v[152:155], v[18:33]
	v_mfma_f32_32x32x16_bf16 v[2:17], v[136:139], v[148:151], v[2:17]
	v_add_u32_e32 v138, 0x10800, v135
	ds_read_b64_tr_b16 v[136:137], v138
	ds_read_b64_tr_b16 v[138:139], v138 offset:256
	s_waitcnt lgkmcnt(0)
	v_mfma_f32_32x32x16_bf16 v[18:33], v[140:143], v[148:151], v[18:33]
	v_add_u32_e32 v142, 0x11800, v135
	ds_read_b64_tr_b16 v[140:141], v142
	ds_read_b64_tr_b16 v[142:143], v142 offset:256
	s_waitcnt lgkmcnt(0)
	s_nop 0
	v_cndmask_b32_e32 v140, 0, v140, vcc
	v_cndmask_b32_e32 v141, 0, v141, vcc
	v_mfma_f32_32x32x16_bf16 v[2:17], v[144:147], v[152:155], v[2:17]
	ds_read_b128 v[148:151], v158
	ds_read_b128 v[152:155], v159
	v_cndmask_b32_e32 v142, 0, v142, vcc
	v_cndmask_b32_e32 v143, 0, v143, vcc
	v_xor_b32_e32 v144, 0x80008000, v140
	v_xor_b32_e32 v145, 0x80008000, v141
	v_xor_b32_e32 v146, 0x80008000, v142
	v_xor_b32_e32 v147, 0x80008000, v143
	s_waitcnt lgkmcnt(0)
	v_mfma_f32_32x32x16_bf16 v[34:49], v[136:139], v[148:151], v[34:49]
	v_mfma_f32_32x32x16_bf16 v[50:65], v[136:139], v[152:155], v[50:65]
	v_mfma_f32_32x32x16_bf16 v[34:49], v[144:147], v[152:155], v[34:49]
	v_mfma_f32_32x32x16_bf16 v[50:65], v[140:143], v[148:151], v[50:65]
	ds_read_b128 v[148:151], v160
	ds_read_b128 v[152:155], v161
	s_waitcnt lgkmcnt(0)
	v_mfma_f32_32x32x16_bf16 v[18:33], v[136:139], v[152:155], v[18:33]
	v_mfma_f32_32x32x16_bf16 v[2:17], v[136:139], v[148:151], v[2:17]
	v_add_u32_e32 v138, 0x10c00, v135
	ds_read_b64_tr_b16 v[136:137], v138
	ds_read_b64_tr_b16 v[138:139], v138 offset:256
	s_waitcnt lgkmcnt(0)
	v_add_u32_e32 v135, 0x11c00, v135
	v_mfma_f32_32x32x16_bf16 v[18:33], v[140:143], v[148:151], v[18:33]
	ds_read_b64_tr_b16 v[140:141], v135
	ds_read_b64_tr_b16 v[142:143], v135 offset:256
	s_waitcnt lgkmcnt(0)
	s_nop 0
	v_cndmask_b32_e32 v140, 0, v140, vcc
	v_cndmask_b32_e32 v141, 0, v141, vcc
	v_cndmask_b32_e32 v142, 0, v142, vcc
	v_mfma_f32_32x32x16_bf16 v[2:17], v[144:147], v[152:155], v[2:17]
	ds_read_b128 v[148:151], v134
	ds_read_b128 v[152:155], v162
	v_cndmask_b32_e32 v143, 0, v143, vcc
	v_xor_b32_e32 v144, 0x80008000, v140
	v_xor_b32_e32 v145, 0x80008000, v141
	v_xor_b32_e32 v146, 0x80008000, v142
	v_xor_b32_e32 v147, 0x80008000, v143
	v_lshlrev_b32_e32 v134, 2, v0
	s_waitcnt lgkmcnt(0)
	v_mfma_f32_32x32x16_bf16 v[34:49], v[136:139], v[148:151], v[34:49]
	v_mul_lo_u32 v135, v134, v131
	s_and_b64 vcc, exec, s[74:75]
	v_mfma_f32_32x32x16_bf16 v[50:65], v[136:139], v[152:155], v[50:65]
	v_mfma_f32_32x32x16_bf16 v[34:49], v[144:147], v[152:155], v[34:49]
	v_mfma_f32_32x32x16_bf16 v[50:65], v[140:143], v[148:151], v[50:65]
	ds_read_b128 v[148:151], v163
	ds_read_b128 v[152:155], v164
	s_waitcnt lgkmcnt(0)
	v_mfma_f32_32x32x16_bf16 v[2:17], v[136:139], v[148:151], v[2:17]
	v_mfma_f32_32x32x16_bf16 v[18:33], v[136:139], v[152:155], v[18:33]
	v_and_b32_e32 v136, 0xffc, v135
	v_cvt_f32_u32_e32 v136, v136
	v_mov_b32_e32 v138, v114
	v_mov_b32_e32 v139, v98
	v_add_u32_e32 v135, v135, v131
	v_mul_f32_e32 v136, 0x39800000, v136
	v_cos_f32_e32 v137, v136
	v_sin_f32_e32 v136, v136
	v_mfma_f32_32x32x16_bf16 v[18:33], v[140:143], v[148:151], v[18:33]
	v_mov_b32_e32 v140, v98
	v_mov_b32_e32 v141, v114
	v_mul_f32_e64 v136, v136, s54
	v_mul_f32_e64 v137, v137, s54
	v_mov_b32_e32 v114, v99
	v_pk_mul_f32 v[138:139], v[136:137], v[138:139]
	v_pk_mul_f32 v[136:137], v[136:137], v[140:141]
	v_sub_f32_e32 v138, v139, v138
	v_add_f32_e32 v98, v136, v137
	v_xor_b32_e32 v137, 0x80000000, v98
	v_and_b32_e32 v98, 0xfff, v135
	v_cvt_f32_u32_e32 v98, v98
	v_add_u32_e32 v135, v135, v131
	v_mfma_f32_32x32x16_bf16 v[2:17], v[144:147], v[152:155], v[2:17]
	v_mov_b32_e32 v144, v104
	v_mul_f32_e32 v98, 0x39800000, v98
	v_cos_f32_e32 v141, v98
	v_sin_f32_e32 v140, v98
	v_mov_b32_e32 v98, v115
	v_mov_b32_e32 v145, v120
	v_pk_mul_f32 v[140:141], v[140:141], s[54:55] op_sel_hi:[1,0]
	s_nop 0
	v_pk_mul_f32 v[142:143], v[140:141], v[98:99]
	v_pk_mul_f32 v[98:99], v[140:141], v[114:115]
	v_sub_f32_e32 v139, v143, v142
	v_add_f32_e32 v98, v98, v99
	v_and_b32_e32 v99, 0xffe, v135
	v_cvt_f32_u32_e32 v99, v99
	v_add_u32_e32 v135, v135, v131
	v_mov_b32_e32 v142, v100
	v_mov_b32_e32 v143, v116
	v_mul_f32_e32 v99, 0x39800000, v99
	v_cos_f32_e32 v115, v99
	v_sin_f32_e32 v114, v99
	v_xor_b32_e32 v98, 0x80000000, v98
	v_pk_mul_f32 v[140:141], v[114:115], s[54:55] op_sel_hi:[1,0]
	v_mov_b32_e32 v115, v100
	v_and_b32_e32 v100, 0xfff, v135
	v_cvt_f32_u32_e32 v100, v100
	v_mov_b32_e32 v114, v116
	v_pk_mul_f32 v[114:115], v[140:141], v[114:115]
	v_pk_mul_f32 v[140:141], v[140:141], v[142:143]
	v_mul_f32_e32 v100, 0x39800000, v100
	v_add_f32_e32 v99, v140, v141
	v_cos_f32_e32 v141, v100
	v_sin_f32_e32 v140, v100
	v_mov_b32_e32 v100, v117
	v_mov_b32_e32 v116, v101
	v_mad_u32_u24 v135, v131, 5, v135
	v_pk_mul_f32 v[140:141], v[140:141], s[54:55] op_sel_hi:[1,0]
	v_sub_f32_e32 v114, v115, v114
	v_pk_mul_f32 v[142:143], v[140:141], v[100:101]
	v_pk_mul_f32 v[100:101], v[140:141], v[116:117]
	v_sub_f32_e32 v115, v143, v142
	v_add_f32_e32 v100, v100, v101
	v_and_b32_e32 v101, 0xffc, v135
	v_cvt_f32_u32_e32 v101, v101
	v_add_u32_e32 v135, v135, v131
	v_mov_b32_e32 v141, v102
	v_mov_b32_e32 v142, v102
	v_mul_f32_e32 v101, 0x39800000, v101
	v_cos_f32_e32 v117, v101
	v_sin_f32_e32 v116, v101
	v_and_b32_e32 v102, 0xfff, v135
	v_cvt_f32_u32_e32 v102, v102
	v_mov_b32_e32 v140, v118
	v_pk_mul_f32 v[116:117], v[116:117], s[54:55] op_sel_hi:[1,0]
	v_mov_b32_e32 v143, v118
	v_pk_mul_f32 v[140:141], v[116:117], v[140:141]
	v_pk_mul_f32 v[116:117], v[116:117], v[142:143]
	v_mul_f32_e32 v102, 0x39800000, v102
	v_add_f32_e32 v101, v116, v117
	v_cos_f32_e32 v117, v102
	v_sin_f32_e32 v116, v102
	v_mov_b32_e32 v102, v119
	v_mov_b32_e32 v118, v103
	v_sub_f32_e32 v140, v141, v140
	v_pk_mul_f32 v[116:117], v[116:117], s[54:55] op_sel_hi:[1,0]
	v_xor_b32_e32 v99, 0x80000000, v99
	v_pk_mul_f32 v[142:143], v[116:117], v[102:103]
	v_pk_mul_f32 v[102:103], v[116:117], v[118:119]
	v_add_u32_e32 v117, v135, v131
	v_add_f32_e32 v102, v102, v103
	v_and_b32_e32 v103, 0xffe, v117
	v_cvt_f32_u32_e32 v103, v103
	v_sub_f32_e32 v141, v143, v142
	v_mov_b32_e32 v142, v120
	v_mov_b32_e32 v143, v104
	v_mul_f32_e32 v103, 0x39800000, v103
	v_cos_f32_e32 v119, v103
	v_sin_f32_e32 v118, v103
	v_mov_b32_e32 v120, v105
	v_xor_b32_e32 v100, 0x80000000, v100
	v_xor_b32_e32 v101, 0x80000000, v101
	v_pk_mul_f32 v[118:119], v[118:119], s[54:55] op_sel_hi:[1,0]
	v_xor_b32_e32 v102, 0x80000000, v102
	v_pk_mul_f32 v[142:143], v[118:119], v[142:143]
	v_pk_mul_f32 v[118:119], v[118:119], v[144:145]
	v_sub_f32_e32 v142, v143, v142
	v_add_f32_e32 v103, v118, v119
	v_add_u32_e32 v118, v117, v131
	v_and_b32_e32 v104, 0xfff, v118
	v_cvt_f32_u32_e32 v104, v104
	v_mad_u32_u24 v136, v131, 5, v118
	v_add_u32_e32 v135, v136, v131
	v_xor_b32_e32 v103, 0x80000000, v103
	v_mul_f32_e32 v104, 0x39800000, v104
	v_cos_f32_e32 v145, v104
	v_sin_f32_e32 v144, v104
	v_mov_b32_e32 v104, v121
	v_pk_mul_f32 v[144:145], v[144:145], s[54:55] op_sel_hi:[1,0]
	s_nop 0
	v_pk_mul_f32 v[146:147], v[144:145], v[104:105]
	v_pk_mul_f32 v[104:105], v[144:145], v[120:121]
	v_mov_b32_e32 v144, v122
	v_add_f32_e32 v104, v104, v105
	v_and_b32_e32 v105, 0xffc, v136
	v_cvt_f32_u32_e32 v105, v105
	v_mov_b32_e32 v145, v106
	v_sub_f32_e32 v143, v147, v146
	v_xor_b32_e32 v104, 0x80000000, v104
	v_mul_f32_e32 v105, 0x39800000, v105
	v_cos_f32_e32 v121, v105
	v_sin_f32_e32 v120, v105
	s_nop 0
	v_pk_mul_f32 v[120:121], v[120:121], s[54:55] op_sel_hi:[1,0]
	s_nop 0
	v_pk_mul_f32 v[144:145], v[120:121], v[144:145]
	s_nop 0
	v_sub_f32_e32 v105, v145, v144
	v_mov_b32_e32 v144, v106
	v_mov_b32_e32 v145, v122
	v_pk_mul_f32 v[120:121], v[120:121], v[144:145]
	v_mov_b32_e32 v122, v107
	v_add_f32_e32 v106, v120, v121
	v_xor_b32_e32 v146, 0x80000000, v106
	v_and_b32_e32 v106, 0xfff, v135
	v_cvt_f32_u32_e32 v106, v106
	v_mul_f32_e32 v106, 0x39800000, v106
	v_cos_f32_e32 v121, v106
	v_sin_f32_e32 v120, v106
	v_mov_b32_e32 v106, v123
	v_pk_mul_f32 v[120:121], v[120:121], s[54:55] op_sel_hi:[1,0]
	s_nop 0
	v_pk_mul_f32 v[144:145], v[120:121], v[106:107]
	v_pk_mul_f32 v[106:107], v[120:121], v[122:123]
	v_add_u32_e32 v123, v135, v131
	v_add_f32_e32 v106, v106, v107
	v_sub_f32_e32 v144, v145, v144
	v_xor_b32_e32 v145, 0x80000000, v106
	v_and_b32_e32 v106, 0xffe, v123
	v_cvt_f32_u32_e32 v106, v106
	v_mov_b32_e32 v120, v124
	v_mov_b32_e32 v121, v108
	v_add_u32_e32 v122, v123, v131
	v_mul_f32_e32 v106, 0x39800000, v106
	v_cos_f32_e32 v107, v106
	v_sin_f32_e32 v106, v106
	s_nop 0
	v_pk_mul_f32 v[106:107], v[106:107], s[54:55] op_sel_hi:[1,0]
	s_nop 0
	v_pk_mul_f32 v[120:121], v[106:107], v[120:121]
	s_nop 0
	v_sub_f32_e32 v147, v121, v120
	v_mov_b32_e32 v120, v108
	v_mov_b32_e32 v121, v124
	v_pk_mul_f32 v[106:107], v[106:107], v[120:121]
	v_mov_b32_e32 v108, v125
	v_add_f32_e32 v106, v106, v107
	v_xor_b32_e32 v148, 0x80000000, v106
	v_and_b32_e32 v106, 0xfff, v122
	v_cvt_f32_u32_e32 v106, v106
	v_mov_b32_e32 v124, v109
	v_mul_f32_e32 v106, 0x39800000, v106
	v_cos_f32_e32 v107, v106
	v_sin_f32_e32 v106, v106
	s_nop 0
	v_pk_mul_f32 v[106:107], v[106:107], s[54:55] op_sel_hi:[1,0]
	s_nop 0
	v_pk_mul_f32 v[120:121], v[106:107], v[108:109]
	v_pk_mul_f32 v[106:107], v[106:107], v[124:125]
	v_sub_f32_e32 v149, v121, v120
	v_add_f32_e32 v106, v106, v107
	v_mad_u32_u24 v121, v131, 5, v122
	v_xor_b32_e32 v124, 0x80000000, v106
	v_and_b32_e32 v106, 0xffc, v121
	v_cvt_f32_u32_e32 v106, v106
	v_mov_b32_e32 v108, v126
	v_mov_b32_e32 v109, v110
	v_add_u32_e32 v120, v121, v131
	v_mul_f32_e32 v106, 0x39800000, v106
	v_cos_f32_e32 v107, v106
	v_sin_f32_e32 v106, v106
	v_add_u32_e32 v119, v120, v131
	v_add_u32_e32 v116, v119, v131
	v_pk_mul_f32 v[106:107], v[106:107], s[54:55] op_sel_hi:[1,0]
	s_nop 0
	v_pk_mul_f32 v[108:109], v[106:107], v[108:109]
	s_nop 0
	v_sub_f32_e32 v125, v109, v108
	v_mov_b32_e32 v108, v110
	v_mov_b32_e32 v109, v126
	v_pk_mul_f32 v[106:107], v[106:107], v[108:109]
	v_mov_b32_e32 v110, v127
	v_add_f32_e32 v106, v106, v107
	v_xor_b32_e32 v150, 0x80000000, v106
	v_and_b32_e32 v106, 0xfff, v120
	v_cvt_f32_u32_e32 v106, v106
	v_mov_b32_e32 v126, v111
	v_mul_f32_e32 v106, 0x39800000, v106
	v_cos_f32_e32 v107, v106
	v_sin_f32_e32 v106, v106
	s_nop 0
	v_pk_mul_f32 v[106:107], v[106:107], s[54:55] op_sel_hi:[1,0]
	s_nop 0
	v_pk_mul_f32 v[108:109], v[106:107], v[110:111]
	v_pk_mul_f32 v[106:107], v[106:107], v[126:127]
	v_sub_f32_e32 v151, v109, v108
	v_add_f32_e32 v106, v106, v107
	v_xor_b32_e32 v126, 0x80000000, v106
	v_and_b32_e32 v106, 0xffe, v119
	v_cvt_f32_u32_e32 v106, v106
	v_mov_b32_e32 v108, v128
	v_mov_b32_e32 v109, v112
	v_mul_f32_e32 v106, 0x39800000, v106
	v_cos_f32_e32 v107, v106
	v_sin_f32_e32 v106, v106
	s_nop 0
	v_pk_mul_f32 v[106:107], v[106:107], s[54:55] op_sel_hi:[1,0]
	s_nop 0
	v_pk_mul_f32 v[108:109], v[106:107], v[108:109]
	s_nop 0
	v_sub_f32_e32 v127, v109, v108
	v_mov_b32_e32 v108, v112
	v_mov_b32_e32 v109, v128
	v_pk_mul_f32 v[106:107], v[106:107], v[108:109]
	v_mov_b32_e32 v112, v129
	v_add_f32_e32 v106, v106, v107
	v_xor_b32_e32 v152, 0x80000000, v106
	v_and_b32_e32 v106, 0xfff, v116
	v_cvt_f32_u32_e32 v106, v106
	v_mov_b32_e32 v128, v113
	v_mul_f32_e32 v106, 0x39800000, v106
	v_cos_f32_e32 v107, v106
	v_sin_f32_e32 v106, v106
	s_nop 0
	v_pk_mul_f32 v[106:107], v[106:107], s[54:55] op_sel_hi:[1,0]
	s_nop 0
	v_pk_mul_f32 v[108:109], v[106:107], v[112:113]
	v_pk_mul_f32 v[106:107], v[106:107], v[128:129]
	v_sub_f32_e32 v153, v109, v108
	v_add_f32_e32 v106, v106, v107
	v_xor_b32_e32 v128, 0x80000000, v106
	v_cvt_pk_bf16_f32 v106, v138, v139
	v_cvt_pk_bf16_f32 v107, v114, v115
	v_or_b32_e32 v115, 32, v131
	v_mul_lo_u32 v114, v134, v115
	v_cvt_pk_bf16_f32 v108, v140, v141
	v_cvt_pk_bf16_f32 v109, v142, v143
	v_cvt_pk_bf16_f32 v110, v137, v98
	v_cvt_pk_bf16_f32 v111, v99, v100
	v_cvt_pk_bf16_f32 v112, v101, v102
	v_cvt_pk_bf16_f32 v113, v103, v104
	v_cvt_pk_bf16_f32 v98, v105, v144
	v_cvt_pk_bf16_f32 v99, v147, v149
	v_cvt_pk_bf16_f32 v100, v125, v151
	v_cvt_pk_bf16_f32 v101, v127, v153
	v_cvt_pk_bf16_f32 v102, v146, v145
	v_cvt_pk_bf16_f32 v103, v148, v124
	v_and_b32_e32 v124, 0xffc, v114
	v_cvt_f32_u32_e32 v124, v124
	v_cvt_pk_bf16_f32 v104, v150, v126
	v_cvt_pk_bf16_f32 v105, v152, v128
	v_mov_b32_e32 v128, v66
	v_mul_f32_e32 v124, 0x39800000, v124
	v_cos_f32_e32 v125, v124
	v_sin_f32_e32 v124, v124
	v_mov_b32_e32 v129, v82
	v_add_u32_e32 v114, v114, v115
	v_mov_b32_e32 v138, v68
	v_pk_mul_f32 v[126:127], v[124:125], s[54:55] op_sel_hi:[1,0]
	v_mov_b32_e32 v124, v82
	v_mov_b32_e32 v125, v66
	v_pk_mul_f32 v[124:125], v[126:127], v[124:125]
	v_pk_mul_f32 v[126:127], v[126:127], v[128:129]
	v_sub_f32_e32 v125, v125, v124
	v_add_f32_e32 v66, v126, v127
	v_xor_b32_e32 v124, 0x80000000, v66
	v_and_b32_e32 v66, 0xfff, v114
	v_cvt_f32_u32_e32 v66, v66
	v_mov_b32_e32 v82, v67
	v_add_u32_e32 v114, v114, v115
	v_mov_b32_e32 v139, v84
	v_mul_f32_e32 v66, 0x39800000, v66
	v_cos_f32_e32 v127, v66
	v_sin_f32_e32 v126, v66
	v_mov_b32_e32 v66, v83
	v_pk_mul_f32 v[128:129], v[126:127], s[54:55] op_sel_hi:[1,0]
	s_nop 0
	v_pk_mul_f32 v[126:127], v[128:129], v[66:67]
	v_pk_mul_f32 v[66:67], v[128:129], v[82:83]
	v_sub_f32_e32 v126, v127, v126
	v_add_f32_e32 v66, v66, v67
	v_and_b32_e32 v67, 0xffe, v114
	v_cvt_f32_u32_e32 v67, v67
	v_add_u32_e32 v114, v114, v115
	v_xor_b32_e32 v66, 0x80000000, v66
	v_mul_f32_e32 v67, 0x39800000, v67
	v_cos_f32_e32 v83, v67
	v_sin_f32_e32 v82, v67
	s_nop 0
	v_pk_mul_f32 v[128:129], v[82:83], s[54:55] op_sel_hi:[1,0]
	v_mov_b32_e32 v83, v68
	v_and_b32_e32 v68, 0xfff, v114
	v_cvt_f32_u32_e32 v68, v68
	v_mov_b32_e32 v82, v84
	v_pk_mul_f32 v[82:83], v[128:129], v[82:83]
	v_pk_mul_f32 v[128:129], v[128:129], v[138:139]
	v_mul_f32_e32 v68, 0x39800000, v68
	v_add_f32_e32 v67, v128, v129
	v_cos_f32_e32 v129, v68
	v_sin_f32_e32 v128, v68
	v_mov_b32_e32 v68, v85
	v_mov_b32_e32 v84, v69
	v_mad_u32_u24 v114, v115, 5, v114
	v_pk_mul_f32 v[128:129], v[128:129], s[54:55] op_sel_hi:[1,0]
	v_sub_f32_e32 v82, v83, v82
	v_pk_mul_f32 v[138:139], v[128:129], v[68:69]
	v_pk_mul_f32 v[68:69], v[128:129], v[84:85]
	v_sub_f32_e32 v83, v139, v138
	v_add_f32_e32 v68, v68, v69
	v_and_b32_e32 v69, 0xffc, v114
	v_cvt_f32_u32_e32 v69, v69
	v_mov_b32_e32 v138, v70
	v_mov_b32_e32 v139, v86
	v_xor_b32_e32 v67, 0x80000000, v67
	v_mul_f32_e32 v69, 0x39800000, v69
	v_cos_f32_e32 v85, v69
	v_sin_f32_e32 v84, v69
	v_xor_b32_e32 v68, 0x80000000, v68
	v_pk_mul_f32 v[128:129], v[84:85], s[54:55] op_sel_hi:[1,0]
	v_mov_b32_e32 v85, v70
	v_add_u32_e32 v70, v114, v115
	v_and_b32_e32 v70, 0xfff, v70
	v_cvt_f32_u32_e32 v70, v70
	v_mov_b32_e32 v84, v86
	v_pk_mul_f32 v[84:85], v[128:129], v[84:85]
	v_pk_mul_f32 v[128:129], v[128:129], v[138:139]
	v_mul_f32_e32 v70, 0x39800000, v70
	v_add_f32_e32 v69, v128, v129
	v_cos_f32_e32 v129, v70
	v_sin_f32_e32 v128, v70
	v_mov_b32_e32 v70, v87
	v_mov_b32_e32 v86, v71
	v_lshlrev_b32_e32 v114, 7, v0
	v_pk_mul_f32 v[128:129], v[128:129], s[54:55] op_sel_hi:[1,0]
	v_sub_f32_e32 v84, v85, v84
	v_pk_mul_f32 v[138:139], v[128:129], v[70:71]
	v_pk_mul_f32 v[70:71], v[128:129], v[86:87]
	v_sub_f32_e32 v85, v139, v138
	v_add_f32_e32 v70, v70, v71
	v_add3_u32 v71, v114, v117, s12
	v_and_b32_e32 v71, 0xffe, v71
	v_cvt_f32_u32_e32 v71, v71
	s_movk_i32 s12, 0x160
	v_mov_b32_e32 v138, v72
	v_mov_b32_e32 v139, v88
	v_mul_f32_e32 v71, 0x39800000, v71
	v_cos_f32_e32 v87, v71
	v_sin_f32_e32 v86, v71
	v_xor_b32_e32 v69, 0x80000000, v69
	v_xor_b32_e32 v70, 0x80000000, v70
	v_pk_mul_f32 v[128:129], v[86:87], s[54:55] op_sel_hi:[1,0]
	v_mov_b32_e32 v87, v72
	v_add3_u32 v72, v114, v118, s12
	v_and_b32_e32 v72, 0xfff, v72
	v_cvt_f32_u32_e32 v72, v72
	v_mov_b32_e32 v86, v88
	v_pk_mul_f32 v[86:87], v[128:129], v[86:87]
	v_pk_mul_f32 v[128:129], v[128:129], v[138:139]
	v_mul_f32_e32 v72, 0x39800000, v72
	v_add_f32_e32 v71, v128, v129
	v_cos_f32_e32 v129, v72
	v_sin_f32_e32 v128, v72
	v_mov_b32_e32 v72, v89
	v_mov_b32_e32 v88, v73
	s_movk_i32 s12, 0x200
	v_pk_mul_f32 v[128:129], v[128:129], s[54:55] op_sel_hi:[1,0]
	v_xor_b32_e32 v71, 0x80000000, v71
	v_pk_mul_f32 v[138:139], v[128:129], v[72:73]
	v_pk_mul_f32 v[72:73], v[128:129], v[88:89]
	v_mov_b32_e32 v128, v90
	v_add_f32_e32 v72, v72, v73
	v_add3_u32 v73, v114, v136, s12
	v_and_b32_e32 v73, 0xffc, v73
	v_cvt_f32_u32_e32 v73, v73
	v_mov_b32_e32 v129, v74
	s_movk_i32 s12, 0x220
	v_sub_f32_e32 v86, v87, v86
	v_mul_f32_e32 v73, 0x39800000, v73
	v_cos_f32_e32 v89, v73
	v_sin_f32_e32 v88, v73
	v_sub_f32_e32 v87, v139, v138
	v_xor_b32_e32 v72, 0x80000000, v72
	v_pk_mul_f32 v[88:89], v[88:89], s[54:55] op_sel_hi:[1,0]
	s_nop 0
	v_pk_mul_f32 v[128:129], v[88:89], v[128:129]
	s_nop 0
	v_sub_f32_e32 v73, v129, v128
	v_mov_b32_e32 v128, v74
	v_mov_b32_e32 v129, v90
	v_pk_mul_f32 v[88:89], v[88:89], v[128:129]
	v_mov_b32_e32 v90, v75
	v_add_f32_e32 v74, v88, v89
	v_xor_b32_e32 v117, 0x80000000, v74
	v_add3_u32 v74, v114, v135, s12
	v_and_b32_e32 v74, 0xfff, v74
	v_cvt_f32_u32_e32 v74, v74
	s_movk_i32 s12, 0x240
	v_mul_f32_e32 v74, 0x39800000, v74
	v_cos_f32_e32 v89, v74
	v_sin_f32_e32 v88, v74
	v_mov_b32_e32 v74, v91
	v_pk_mul_f32 v[88:89], v[88:89], s[54:55] op_sel_hi:[1,0]
	s_nop 0
	v_pk_mul_f32 v[128:129], v[88:89], v[74:75]
	v_pk_mul_f32 v[74:75], v[88:89], v[90:91]
	v_mov_b32_e32 v88, v92
	v_add_f32_e32 v74, v74, v75
	v_xor_b32_e32 v90, 0x80000000, v74
	v_add3_u32 v74, v114, v123, s12
	v_and_b32_e32 v74, 0xffe, v74
	v_cvt_f32_u32_e32 v74, v74
	v_mov_b32_e32 v89, v76
	s_movk_i32 s12, 0x260
	v_sub_f32_e32 v118, v129, v128
	v_mul_f32_e32 v74, 0x39800000, v74
	v_cos_f32_e32 v75, v74
	v_sin_f32_e32 v74, v74
	s_nop 0
	v_pk_mul_f32 v[74:75], v[74:75], s[54:55] op_sel_hi:[1,0]
	s_nop 0
	v_pk_mul_f32 v[88:89], v[74:75], v[88:89]
	s_nop 0
	v_sub_f32_e32 v91, v89, v88
	v_mov_b32_e32 v88, v76
	v_mov_b32_e32 v89, v92
	v_pk_mul_f32 v[74:75], v[74:75], v[88:89]
	v_mov_b32_e32 v76, v93
	v_add_f32_e32 v74, v74, v75
	v_xor_b32_e32 v123, 0x80000000, v74
	v_add3_u32 v74, v114, v122, s12
	v_and_b32_e32 v74, 0xfff, v74
	v_cvt_f32_u32_e32 v74, v74
	v_mov_b32_e32 v92, v77
	s_movk_i32 s12, 0x300
	v_mul_f32_e32 v74, 0x39800000, v74
	v_cos_f32_e32 v75, v74
	v_sin_f32_e32 v74, v74
	s_nop 0
	v_pk_mul_f32 v[74:75], v[74:75], s[54:55] op_sel_hi:[1,0]
	s_nop 0
	v_pk_mul_f32 v[88:89], v[74:75], v[76:77]
	v_pk_mul_f32 v[74:75], v[74:75], v[92:93]
	v_sub_f32_e32 v88, v89, v88
	v_add_f32_e32 v74, v74, v75
	v_xor_b32_e32 v89, 0x80000000, v74
	v_add3_u32 v74, v114, v121, s12
	v_and_b32_e32 v74, 0xffc, v74
	v_cvt_f32_u32_e32 v74, v74
	v_mov_b32_e32 v76, v94
	v_mov_b32_e32 v77, v78
	s_movk_i32 s12, 0x320
	v_mul_f32_e32 v74, 0x39800000, v74
	v_cos_f32_e32 v75, v74
	v_sin_f32_e32 v74, v74
	s_nop 0
	v_pk_mul_f32 v[74:75], v[74:75], s[54:55] op_sel_hi:[1,0]
	s_nop 0
	v_pk_mul_f32 v[76:77], v[74:75], v[76:77]
	s_nop 0
	v_sub_f32_e32 v92, v77, v76
	v_mov_b32_e32 v76, v78
	v_mov_b32_e32 v77, v94
	v_pk_mul_f32 v[74:75], v[74:75], v[76:77]
	v_mov_b32_e32 v78, v95
	v_add_f32_e32 v74, v74, v75
	v_xor_b32_e32 v93, 0x80000000, v74
	v_add3_u32 v74, v114, v120, s12
	v_and_b32_e32 v74, 0xfff, v74
	v_cvt_f32_u32_e32 v74, v74
	v_mov_b32_e32 v94, v79
	s_movk_i32 s12, 0x340
	v_mul_f32_e32 v74, 0x39800000, v74
	v_cos_f32_e32 v75, v74
	v_sin_f32_e32 v74, v74
	s_nop 0
	v_pk_mul_f32 v[74:75], v[74:75], s[54:55] op_sel_hi:[1,0]
	s_nop 0
	v_pk_mul_f32 v[76:77], v[74:75], v[78:79]
	v_pk_mul_f32 v[74:75], v[74:75], v[94:95]
	v_sub_f32_e32 v120, v77, v76
	v_add_f32_e32 v74, v74, v75
	v_xor_b32_e32 v94, 0x80000000, v74
	v_add3_u32 v74, v114, v119, s12
	v_and_b32_e32 v74, 0xffe, v74
	v_cvt_f32_u32_e32 v74, v74
	v_mov_b32_e32 v76, v96
	v_mov_b32_e32 v77, v80
	s_movk_i32 s12, 0x360
	v_mul_f32_e32 v74, 0x39800000, v74
	v_cos_f32_e32 v75, v74
	v_sin_f32_e32 v74, v74
	s_nop 0
	v_pk_mul_f32 v[74:75], v[74:75], s[54:55] op_sel_hi:[1,0]
	s_nop 0
	v_pk_mul_f32 v[76:77], v[74:75], v[76:77]
	s_nop 0
	v_sub_f32_e32 v95, v77, v76
	v_mov_b32_e32 v76, v80
	v_mov_b32_e32 v77, v96
	v_pk_mul_f32 v[74:75], v[74:75], v[76:77]
	v_mov_b32_e32 v80, v97
	v_add_f32_e32 v74, v74, v75
	v_xor_b32_e32 v119, 0x80000000, v74
	v_add3_u32 v74, v114, v116, s12
	v_and_b32_e32 v74, 0xfff, v74
	v_cvt_f32_u32_e32 v74, v74
	v_mov_b32_e32 v96, v81
	s_movk_i32 s12, 0x540
	v_mul_f32_e32 v74, 0x39800000, v74
	v_cos_f32_e32 v75, v74
	v_sin_f32_e32 v74, v74
	s_nop 0
	v_pk_mul_f32 v[74:75], v[74:75], s[54:55] op_sel_hi:[1,0]
	s_nop 0
	v_pk_mul_f32 v[76:77], v[74:75], v[80:81]
	v_pk_mul_f32 v[74:75], v[74:75], v[96:97]
	v_sub_f32_e32 v121, v77, v76
	v_add_f32_e32 v74, v74, v75
	v_xor_b32_e32 v96, 0x80000000, v74
	v_cvt_pk_bf16_f32 v74, v125, v126
	v_cvt_pk_bf16_f32 v75, v82, v83
	v_cvt_pk_bf16_f32 v76, v84, v85
	v_cvt_pk_bf16_f32 v77, v86, v87
	v_cvt_pk_bf16_f32 v78, v124, v66
	v_cvt_pk_bf16_f32 v79, v67, v68
	v_cvt_pk_bf16_f32 v80, v69, v70
	v_cvt_pk_bf16_f32 v81, v71, v72
	v_cvt_pk_bf16_f32 v66, v73, v118
	v_cvt_pk_bf16_f32 v67, v91, v88
	v_cvt_pk_bf16_f32 v68, v92, v120
	v_cvt_pk_bf16_f32 v69, v95, v121
	v_cvt_pk_bf16_f32 v70, v117, v90
	v_cvt_pk_bf16_f32 v71, v123, v89
	v_mad_u32_u24 v89, v131, 5, v116
	v_and_b32_e32 v82, 0xffc, v89
	v_cvt_f32_u32_e32 v82, v82
	v_mov_b32_e32 v86, v34
	v_mov_b32_e32 v87, v50
	v_add_u32_e32 v116, 33, v134
	v_mul_f32_e32 v82, 0x39800000, v82
	v_cos_f32_e32 v83, v82
	v_sin_f32_e32 v82, v82
	v_mul_lo_u32 v88, v116, v131
	v_cvt_pk_bf16_f32 v72, v93, v94
	v_cvt_pk_bf16_f32 v73, v119, v96
	v_pk_mul_f32 v[84:85], v[82:83], s[54:55] op_sel_hi:[1,0]
	v_mov_b32_e32 v82, v50
	v_mov_b32_e32 v83, v34
	v_pk_mul_f32 v[82:83], v[84:85], v[82:83]
	v_pk_mul_f32 v[84:85], v[84:85], v[86:87]
	v_sub_f32_e32 v83, v83, v82
	v_add_f32_e32 v34, v84, v85
	v_xor_b32_e32 v82, 0x80000000, v34
	v_and_b32_e32 v34, 0xfff, v88
	v_cvt_f32_u32_e32 v34, v34
	v_mov_b32_e32 v50, v35
	v_add_u32_e32 v88, v88, v131
	v_add_u32_e32 v117, 32, v134
	v_mul_f32_e32 v34, 0x39800000, v34
	v_cos_f32_e32 v85, v34
	v_sin_f32_e32 v84, v34
	v_mov_b32_e32 v34, v51
	v_pk_mul_f32 v[86:87], v[84:85], s[54:55] op_sel_hi:[1,0]
	s_nop 0
	v_pk_mul_f32 v[84:85], v[86:87], v[34:35]
	v_pk_mul_f32 v[34:35], v[86:87], v[50:51]
	v_sub_f32_e32 v85, v85, v84
	v_add_f32_e32 v34, v34, v35
	v_xor_b32_e32 v84, 0x80000000, v34
	v_and_b32_e32 v34, 0xffe, v88
	v_cvt_f32_u32_e32 v34, v34
	v_mov_b32_e32 v50, v52
	v_mov_b32_e32 v51, v36
	v_cvt_pk_bf16_f32 v90, v83, v85
	v_mul_f32_e32 v34, 0x39800000, v34
	v_cos_f32_e32 v35, v34
	v_sin_f32_e32 v34, v34
	s_nop 0
	v_pk_mul_f32 v[34:35], v[34:35], s[54:55] op_sel_hi:[1,0]
	s_nop 0
	v_pk_mul_f32 v[50:51], v[34:35], v[50:51]
	s_nop 0
	v_sub_f32_e32 v87, v51, v50
	v_mov_b32_e32 v50, v36
	v_mov_b32_e32 v51, v52
	v_pk_mul_f32 v[34:35], v[34:35], v[50:51]
	v_mov_b32_e32 v36, v53
	v_add_f32_e32 v34, v34, v35
	v_xor_b32_e32 v86, 0x80000000, v34
	v_add_u32_e32 v34, v88, v131
	v_and_b32_e32 v34, 0xfff, v34
	v_cvt_f32_u32_e32 v34, v34
	v_mov_b32_e32 v52, v37
	v_mul_f32_e32 v34, 0x39800000, v34
	v_cos_f32_e32 v35, v34
	v_sin_f32_e32 v34, v34
	s_nop 0
	v_pk_mul_f32 v[34:35], v[34:35], s[54:55] op_sel_hi:[1,0]
	s_nop 0
	v_pk_mul_f32 v[50:51], v[34:35], v[36:37]
	v_pk_mul_f32 v[34:35], v[34:35], v[52:53]
	v_sub_f32_e32 v88, v51, v50
	v_add_f32_e32 v34, v34, v35
	v_lshl_add_u32 v50, v131, 3, v89
	v_xor_b32_e32 v52, 0x80000000, v34
	v_and_b32_e32 v34, 0xffc, v50
	v_cvt_f32_u32_e32 v34, v34
	v_mov_b32_e32 v36, v54
	v_mov_b32_e32 v37, v38
	v_add_u32_e32 v50, v50, v131
	v_mul_f32_e32 v34, 0x39800000, v34
	v_cos_f32_e32 v35, v34
	v_sin_f32_e32 v34, v34
	v_add_u32_e32 v51, v50, v131
	v_cvt_pk_bf16_f32 v91, v87, v88
	v_pk_mul_f32 v[34:35], v[34:35], s[54:55] op_sel_hi:[1,0]
	s_nop 0
	v_pk_mul_f32 v[36:37], v[34:35], v[36:37]
	s_nop 0
	v_sub_f32_e32 v89, v37, v36
	v_mov_b32_e32 v36, v38
	v_mov_b32_e32 v37, v54
	v_pk_mul_f32 v[34:35], v[34:35], v[36:37]
	v_mov_b32_e32 v38, v55
	v_add_f32_e32 v34, v34, v35
	v_xor_b32_e32 v53, 0x80000000, v34
	v_and_b32_e32 v34, 0xfff, v50
	v_cvt_f32_u32_e32 v34, v34
	v_mov_b32_e32 v54, v39
	v_add_u32_e32 v50, v51, v131
	v_mul_f32_e32 v34, 0x39800000, v34
	v_cos_f32_e32 v35, v34
	v_sin_f32_e32 v34, v34
	s_nop 0
	v_pk_mul_f32 v[34:35], v[34:35], s[54:55] op_sel_hi:[1,0]
	s_nop 0
	v_pk_mul_f32 v[36:37], v[34:35], v[38:39]
	v_pk_mul_f32 v[34:35], v[34:35], v[54:55]
	v_sub_f32_e32 v92, v37, v36
	v_add_f32_e32 v34, v34, v35
	v_xor_b32_e32 v54, 0x80000000, v34
	v_and_b32_e32 v34, 0xffe, v51
	v_cvt_f32_u32_e32 v34, v34
	v_mov_b32_e32 v36, v56
	v_mov_b32_e32 v37, v40
	v_cvt_pk_bf16_f32 v92, v89, v92
	v_mul_f32_e32 v34, 0x39800000, v34
	v_cos_f32_e32 v35, v34
	v_sin_f32_e32 v34, v34
	s_nop 0
	v_pk_mul_f32 v[34:35], v[34:35], s[54:55] op_sel_hi:[1,0]
	s_nop 0
	v_pk_mul_f32 v[36:37], v[34:35], v[36:37]
	s_nop 0
	v_sub_f32_e32 v93, v37, v36
	v_mov_b32_e32 v36, v40
	v_mov_b32_e32 v37, v56
	v_pk_mul_f32 v[34:35], v[34:35], v[36:37]
	v_mov_b32_e32 v40, v57
	v_add_f32_e32 v34, v34, v35
	v_xor_b32_e32 v55, 0x80000000, v34
	v_and_b32_e32 v34, 0xfff, v50
	v_cvt_f32_u32_e32 v34, v34
	v_mov_b32_e32 v56, v41
	v_mul_f32_e32 v34, 0x39800000, v34
	v_cos_f32_e32 v35, v34
	v_sin_f32_e32 v34, v34
	s_nop 0
	v_pk_mul_f32 v[34:35], v[34:35], s[54:55] op_sel_hi:[1,0]
	s_nop 0
	v_pk_mul_f32 v[36:37], v[34:35], v[40:41]
	v_pk_mul_f32 v[34:35], v[34:35], v[56:57]
	v_mad_u32_u24 v41, v131, 5, v50
	v_add_f32_e32 v34, v34, v35
	v_xor_b32_e32 v56, 0x80000000, v34
	v_and_b32_e32 v34, 0xffc, v41
	v_cvt_f32_u32_e32 v34, v34
	v_sub_f32_e32 v94, v37, v36
	v_mov_b32_e32 v36, v58
	v_mov_b32_e32 v37, v42
	v_mul_f32_e32 v34, 0x39800000, v34
	v_cos_f32_e32 v35, v34
	v_sin_f32_e32 v34, v34
	v_add_u32_e32 v40, v41, v131
	v_add_u32_e32 v39, v40, v131
	v_add_u32_e32 v38, v39, v131
	v_pk_mul_f32 v[34:35], v[34:35], s[54:55] op_sel_hi:[1,0]
	v_cvt_pk_bf16_f32 v93, v93, v94
	v_cvt_pk_bf16_f32 v94, v82, v84
	v_cvt_pk_bf16_f32 v95, v86, v52
	v_mul_lo_u32 v52, v117, v115
	v_pk_mul_f32 v[36:37], v[34:35], v[36:37]
	v_cvt_pk_bf16_f32 v96, v53, v54
	v_cvt_pk_bf16_f32 v97, v55, v56
	s_nop 0
	v_sub_f32_e32 v57, v37, v36
	v_mov_b32_e32 v36, v42
	v_mov_b32_e32 v37, v58
	v_pk_mul_f32 v[34:35], v[34:35], v[36:37]
	v_mov_b32_e32 v42, v59
	v_add_f32_e32 v34, v34, v35
	v_xor_b32_e32 v118, 0x80000000, v34
	v_and_b32_e32 v34, 0xfff, v40
	v_cvt_f32_u32_e32 v34, v34
	v_mov_b32_e32 v58, v43
	v_mul_f32_e32 v34, 0x39800000, v34
	v_cos_f32_e32 v35, v34
	v_sin_f32_e32 v34, v34
	s_nop 0
	v_pk_mul_f32 v[34:35], v[34:35], s[54:55] op_sel_hi:[1,0]
	s_nop 0
	v_pk_mul_f32 v[36:37], v[34:35], v[42:43]
	v_pk_mul_f32 v[34:35], v[34:35], v[58:59]
	v_sub_f32_e32 v119, v37, v36
	v_add_f32_e32 v34, v34, v35
	v_xor_b32_e32 v58, 0x80000000, v34
	v_and_b32_e32 v34, 0xffe, v39
	v_cvt_f32_u32_e32 v34, v34
	v_mov_b32_e32 v36, v60
	v_mov_b32_e32 v37, v44
	v_mov_b32_e32 v42, v62
	v_mul_f32_e32 v34, 0x39800000, v34
	v_cos_f32_e32 v35, v34
	v_sin_f32_e32 v34, v34
	v_mov_b32_e32 v43, v46
	v_cvt_pk_bf16_f32 v82, v57, v119
	v_pk_mul_f32 v[34:35], v[34:35], s[54:55] op_sel_hi:[1,0]
	s_nop 0
	v_pk_mul_f32 v[36:37], v[34:35], v[36:37]
	s_nop 0
	v_sub_f32_e32 v59, v37, v36
	v_mov_b32_e32 v36, v44
	v_mov_b32_e32 v37, v60
	v_pk_mul_f32 v[34:35], v[34:35], v[36:37]
	v_mov_b32_e32 v44, v61
	v_add_f32_e32 v34, v34, v35
	v_xor_b32_e32 v120, 0x80000000, v34
	v_and_b32_e32 v34, 0xfff, v38
	v_cvt_f32_u32_e32 v34, v34
	v_mov_b32_e32 v60, v45
	v_mul_f32_e32 v34, 0x39800000, v34
	v_cos_f32_e32 v35, v34
	v_sin_f32_e32 v34, v34
	s_nop 0
	v_pk_mul_f32 v[34:35], v[34:35], s[54:55] op_sel_hi:[1,0]
	s_nop 0
	v_pk_mul_f32 v[36:37], v[34:35], v[44:45]
	v_pk_mul_f32 v[34:35], v[34:35], v[60:61]
	v_sub_f32_e32 v121, v37, v36
	v_add_f32_e32 v34, v34, v35
	v_mad_u32_u24 v37, v131, 5, v38
	v_xor_b32_e32 v60, 0x80000000, v34
	v_and_b32_e32 v34, 0xffc, v37
	v_cvt_f32_u32_e32 v34, v34
	v_add_u32_e32 v36, v37, v131
	v_mov_b32_e32 v44, v64
	v_mov_b32_e32 v45, v48
	v_mul_f32_e32 v34, 0x39800000, v34
	v_cos_f32_e32 v35, v34
	v_sin_f32_e32 v34, v34
	v_cvt_pk_bf16_f32 v83, v59, v121
	s_nop 0
	v_pk_mul_f32 v[34:35], v[34:35], s[54:55] op_sel_hi:[1,0]
	s_nop 0
	v_pk_mul_f32 v[42:43], v[34:35], v[42:43]
	s_nop 0
	v_sub_f32_e32 v61, v43, v42
	v_mov_b32_e32 v42, v46
	v_mov_b32_e32 v43, v62
	v_pk_mul_f32 v[34:35], v[34:35], v[42:43]
	v_mov_b32_e32 v46, v63
	v_add_f32_e32 v34, v34, v35
	v_xor_b32_e32 v122, 0x80000000, v34
	v_and_b32_e32 v34, 0xfff, v36
	v_cvt_f32_u32_e32 v34, v34
	v_mov_b32_e32 v62, v47
	v_mul_f32_e32 v34, 0x39800000, v34
	v_cos_f32_e32 v35, v34
	v_sin_f32_e32 v34, v34
	s_nop 0
	v_pk_mul_f32 v[34:35], v[34:35], s[54:55] op_sel_hi:[1,0]
	s_nop 0
	v_pk_mul_f32 v[42:43], v[34:35], v[46:47]
	v_pk_mul_f32 v[34:35], v[34:35], v[62:63]
	v_sub_f32_e32 v46, v43, v42
	v_add_f32_e32 v34, v34, v35
	v_add_u32_e32 v35, v36, v131
	v_xor_b32_e32 v47, 0x80000000, v34
	v_and_b32_e32 v34, 0xffe, v35
	v_cvt_f32_u32_e32 v34, v34
	v_cvt_pk_bf16_f32 v84, v61, v46
	v_mov_b32_e32 v46, v2
	v_mul_f32_e32 v34, 0x39800000, v34
	v_cos_f32_e32 v43, v34
	v_sin_f32_e32 v42, v34
	s_nop 0
	v_pk_mul_f32 v[42:43], v[42:43], s[54:55] op_sel_hi:[1,0]
	s_nop 0
	v_pk_mul_f32 v[44:45], v[42:43], v[44:45]
	s_nop 0
	v_sub_f32_e32 v62, v45, v44
	v_mov_b32_e32 v44, v48
	v_mov_b32_e32 v45, v64
	v_pk_mul_f32 v[42:43], v[42:43], v[44:45]
	v_mov_b32_e32 v48, v65
	v_add_f32_e32 v34, v42, v43
	v_xor_b32_e32 v63, 0x80000000, v34
	v_add_u32_e32 v34, v35, v131
	v_and_b32_e32 v42, 0xfff, v34
	v_cvt_f32_u32_e32 v42, v42
	v_mov_b32_e32 v64, v49
	v_mul_f32_e32 v42, 0x39800000, v42
	v_cos_f32_e32 v43, v42
	v_sin_f32_e32 v42, v42
	s_nop 0
	v_pk_mul_f32 v[42:43], v[42:43], s[54:55] op_sel_hi:[1,0]
	s_nop 0
	v_pk_mul_f32 v[44:45], v[42:43], v[48:49]
	v_pk_mul_f32 v[42:43], v[42:43], v[64:65]
	v_sub_f32_e32 v44, v45, v44
	v_add_f32_e32 v42, v42, v43
	v_xor_b32_e32 v42, 0x80000000, v42
	v_cvt_pk_bf16_f32 v85, v62, v44
	v_cvt_pk_bf16_f32 v86, v118, v58
	v_cvt_pk_bf16_f32 v87, v120, v60
	v_cvt_pk_bf16_f32 v88, v122, v47
	v_cvt_pk_bf16_f32 v89, v63, v42
	v_and_b32_e32 v42, 0xffc, v52
	v_cvt_f32_u32_e32 v42, v42
	v_mov_b32_e32 v47, v18
	v_mul_lo_u32 v48, v116, v115
	v_mov_b32_e32 v49, v20
	v_mul_f32_e32 v42, 0x39800000, v42
	v_cos_f32_e32 v43, v42
	v_sin_f32_e32 v42, v42
	s_nop 0
	v_pk_mul_f32 v[44:45], v[42:43], s[54:55] op_sel_hi:[1,0]
	v_mov_b32_e32 v42, v18
	v_mov_b32_e32 v43, v2
	v_pk_mul_f32 v[42:43], v[44:45], v[42:43]
	v_pk_mul_f32 v[44:45], v[44:45], v[46:47]
	v_sub_f32_e32 v43, v43, v42
	v_add_f32_e32 v2, v44, v45
	v_xor_b32_e32 v42, 0x80000000, v2
	v_and_b32_e32 v2, 0xfff, v48
	v_cvt_f32_u32_e32 v2, v2
	v_mov_b32_e32 v18, v3
	v_mul_f32_e32 v2, 0x39800000, v2
	v_cos_f32_e32 v45, v2
	v_sin_f32_e32 v44, v2
	v_mov_b32_e32 v2, v19
	v_pk_mul_f32 v[46:47], v[44:45], s[54:55] op_sel_hi:[1,0]
	s_nop 0
	v_pk_mul_f32 v[44:45], v[46:47], v[2:3]
	v_pk_mul_f32 v[2:3], v[46:47], v[18:19]
	v_sub_f32_e32 v44, v45, v44
	v_add_u32_e32 v45, v48, v115
	v_add_f32_e32 v2, v2, v3
	v_and_b32_e32 v3, 0xffe, v45
	v_cvt_f32_u32_e32 v3, v3
	v_mov_b32_e32 v48, v4
	v_xor_b32_e32 v2, 0x80000000, v2
	v_cvt_pk_bf16_f32 v122, v43, v44
	v_mul_f32_e32 v3, 0x39800000, v3
	v_cos_f32_e32 v19, v3
	v_sin_f32_e32 v18, v3
	s_nop 0
	v_pk_mul_f32 v[46:47], v[18:19], s[54:55] op_sel_hi:[1,0]
	v_mov_b32_e32 v19, v4
	v_add_u32_e32 v4, v45, v115
	v_and_b32_e32 v4, 0xfff, v4
	v_cvt_f32_u32_e32 v4, v4
	v_mov_b32_e32 v18, v20
	v_pk_mul_f32 v[18:19], v[46:47], v[18:19]
	v_pk_mul_f32 v[46:47], v[46:47], v[48:49]
	v_mul_f32_e32 v4, 0x39800000, v4
	v_add_f32_e32 v3, v46, v47
	v_cos_f32_e32 v47, v4
	v_sin_f32_e32 v46, v4
	v_mov_b32_e32 v4, v21
	v_mov_b32_e32 v20, v5
	v_lshl_add_u32 v45, v115, 3, v52
	v_pk_mul_f32 v[46:47], v[46:47], s[54:55] op_sel_hi:[1,0]
	v_sub_f32_e32 v18, v19, v18
	v_pk_mul_f32 v[48:49], v[46:47], v[4:5]
	v_pk_mul_f32 v[4:5], v[46:47], v[20:21]
	v_sub_f32_e32 v19, v49, v48
	v_add_f32_e32 v4, v4, v5
	v_and_b32_e32 v5, 0xffc, v45
	v_cvt_f32_u32_e32 v5, v5
	v_mov_b32_e32 v48, v6
	v_mov_b32_e32 v49, v22
	v_xor_b32_e32 v3, 0x80000000, v3
	v_mul_f32_e32 v5, 0x39800000, v5
	v_cos_f32_e32 v21, v5
	v_sin_f32_e32 v20, v5
	v_xor_b32_e32 v4, 0x80000000, v4
	v_cvt_pk_bf16_f32 v123, v18, v19
	v_pk_mul_f32 v[46:47], v[20:21], s[54:55] op_sel_hi:[1,0]
	v_mov_b32_e32 v21, v6
	v_add_u32_e32 v6, v45, v115
	v_and_b32_e32 v6, 0xfff, v6
	v_cvt_f32_u32_e32 v6, v6
	v_mov_b32_e32 v20, v22
	v_pk_mul_f32 v[20:21], v[46:47], v[20:21]
	v_pk_mul_f32 v[46:47], v[46:47], v[48:49]
	v_mul_f32_e32 v6, 0x39800000, v6
	v_add_f32_e32 v5, v46, v47
	v_cos_f32_e32 v47, v6
	v_sin_f32_e32 v46, v6
	v_mov_b32_e32 v6, v23
	v_mov_b32_e32 v22, v7
	v_sub_f32_e32 v20, v21, v20
	v_pk_mul_f32 v[46:47], v[46:47], s[54:55] op_sel_hi:[1,0]
	v_xor_b32_e32 v5, 0x80000000, v5
	v_pk_mul_f32 v[48:49], v[46:47], v[6:7]
	v_pk_mul_f32 v[6:7], v[46:47], v[22:23]
	v_sub_f32_e32 v21, v49, v48
	v_add_f32_e32 v6, v6, v7
	v_add3_u32 v7, v114, v51, s12
	v_and_b32_e32 v7, 0xffe, v7
	v_cvt_f32_u32_e32 v7, v7
	s_movk_i32 s12, 0x560
	v_mov_b32_e32 v48, v8
	v_mov_b32_e32 v49, v24
	v_mul_f32_e32 v7, 0x39800000, v7
	v_cos_f32_e32 v23, v7
	v_sin_f32_e32 v22, v7
	v_xor_b32_e32 v6, 0x80000000, v6
	v_cvt_pk_bf16_f32 v124, v20, v21
	v_pk_mul_f32 v[46:47], v[22:23], s[54:55] op_sel_hi:[1,0]
	v_mov_b32_e32 v23, v8
	v_add3_u32 v8, v114, v50, s12
	v_and_b32_e32 v8, 0xfff, v8
	v_cvt_f32_u32_e32 v8, v8
	v_mov_b32_e32 v22, v24
	v_pk_mul_f32 v[22:23], v[46:47], v[22:23]
	v_pk_mul_f32 v[46:47], v[46:47], v[48:49]
	v_mul_f32_e32 v8, 0x39800000, v8
	v_add_f32_e32 v7, v46, v47
	v_cos_f32_e32 v47, v8
	v_sin_f32_e32 v46, v8
	v_mov_b32_e32 v8, v25
	v_mov_b32_e32 v24, v9
	s_movk_i32 s12, 0x620
	v_pk_mul_f32 v[46:47], v[46:47], s[54:55] op_sel_hi:[1,0]
	v_sub_f32_e32 v22, v23, v22
	v_pk_mul_f32 v[48:49], v[46:47], v[8:9]
	v_pk_mul_f32 v[8:9], v[46:47], v[24:25]
	v_mov_b32_e32 v46, v26
	v_add_f32_e32 v8, v8, v9
	v_add3_u32 v9, v114, v41, s88
	v_and_b32_e32 v9, 0xffc, v9
	v_cvt_f32_u32_e32 v9, v9
	v_mov_b32_e32 v47, v10
	v_xor_b32_e32 v7, 0x80000000, v7
	v_sub_f32_e32 v23, v49, v48
	v_mul_f32_e32 v9, 0x39800000, v9
	v_cos_f32_e32 v25, v9
	v_sin_f32_e32 v24, v9
	v_xor_b32_e32 v8, 0x80000000, v8
	v_cvt_pk_bf16_f32 v125, v22, v23
	v_cvt_pk_bf16_f32 v126, v42, v2
	v_pk_mul_f32 v[24:25], v[24:25], s[54:55] op_sel_hi:[1,0]
	v_cvt_pk_bf16_f32 v127, v3, v4
	v_cvt_pk_bf16_f32 v128, v5, v6
	v_cvt_pk_bf16_f32 v129, v7, v8
	s_nop 0
	v_pk_mul_f32 v[46:47], v[24:25], v[46:47]
	s_nop 0
	v_sub_f32_e32 v9, v47, v46
	v_mov_b32_e32 v46, v10
	v_mov_b32_e32 v47, v26
	v_pk_mul_f32 v[24:25], v[24:25], v[46:47]
	v_mov_b32_e32 v26, v11
	v_add_f32_e32 v10, v24, v25
	v_xor_b32_e32 v45, 0x80000000, v10
	v_add3_u32 v10, v114, v40, s12
	v_and_b32_e32 v10, 0xfff, v10
	v_cvt_f32_u32_e32 v10, v10
	s_movk_i32 s12, 0x640
	v_mul_f32_e32 v10, 0x39800000, v10
	v_cos_f32_e32 v25, v10
	v_sin_f32_e32 v24, v10
	v_mov_b32_e32 v10, v27
	v_pk_mul_f32 v[24:25], v[24:25], s[54:55] op_sel_hi:[1,0]
	s_nop 0
	v_pk_mul_f32 v[40:41], v[24:25], v[10:11]
	v_pk_mul_f32 v[10:11], v[24:25], v[26:27]
	v_mov_b32_e32 v24, v28
	v_add_f32_e32 v10, v10, v11
	v_xor_b32_e32 v26, 0x80000000, v10
	v_add3_u32 v10, v114, v39, s12
	v_and_b32_e32 v10, 0xffe, v10
	v_cvt_f32_u32_e32 v10, v10
	v_mov_b32_e32 v25, v12
	s_movk_i32 s12, 0x660
	v_sub_f32_e32 v40, v41, v40
	v_mul_f32_e32 v10, 0x39800000, v10
	v_cos_f32_e32 v11, v10
	v_sin_f32_e32 v10, v10
	s_nop 0
	v_pk_mul_f32 v[10:11], v[10:11], s[54:55] op_sel_hi:[1,0]
	s_nop 0
	v_pk_mul_f32 v[24:25], v[10:11], v[24:25]
	s_nop 0
	v_sub_f32_e32 v27, v25, v24
	v_mov_b32_e32 v24, v12
	v_mov_b32_e32 v25, v28
	v_pk_mul_f32 v[10:11], v[10:11], v[24:25]
	v_mov_b32_e32 v12, v29
	v_add_f32_e32 v10, v10, v11
	v_xor_b32_e32 v39, 0x80000000, v10
	v_add3_u32 v10, v114, v38, s12
	v_and_b32_e32 v10, 0xfff, v10
	v_cvt_f32_u32_e32 v10, v10
	v_mov_b32_e32 v28, v13
	s_movk_i32 s12, 0x700
	v_mul_f32_e32 v10, 0x39800000, v10
	v_cos_f32_e32 v11, v10
	v_sin_f32_e32 v10, v10
	s_nop 0
	v_pk_mul_f32 v[10:11], v[10:11], s[54:55] op_sel_hi:[1,0]
	s_nop 0
	v_pk_mul_f32 v[24:25], v[10:11], v[12:13]
	v_pk_mul_f32 v[10:11], v[10:11], v[28:29]
	v_sub_f32_e32 v24, v25, v24
	v_add_f32_e32 v10, v10, v11
	v_xor_b32_e32 v25, 0x80000000, v10
	v_add3_u32 v10, v114, v37, s12
	v_and_b32_e32 v10, 0xffc, v10
	v_cvt_f32_u32_e32 v10, v10
	v_mov_b32_e32 v12, v30
	v_mov_b32_e32 v13, v14
	s_movk_i32 s12, 0x720
	v_mul_f32_e32 v10, 0x39800000, v10
	v_cos_f32_e32 v11, v10
	v_sin_f32_e32 v10, v10
	s_nop 0
	v_pk_mul_f32 v[10:11], v[10:11], s[54:55] op_sel_hi:[1,0]
	s_nop 0
	v_pk_mul_f32 v[12:13], v[10:11], v[12:13]
	s_nop 0
	v_sub_f32_e32 v28, v13, v12
	v_mov_b32_e32 v12, v14
	v_mov_b32_e32 v13, v30
	v_pk_mul_f32 v[10:11], v[10:11], v[12:13]
	v_mov_b32_e32 v14, v31
	v_add_f32_e32 v10, v10, v11
	v_xor_b32_e32 v29, 0x80000000, v10
	v_add3_u32 v10, v114, v36, s12
	v_and_b32_e32 v10, 0xfff, v10
	v_cvt_f32_u32_e32 v10, v10
	v_mov_b32_e32 v30, v15
	s_movk_i32 s12, 0x740
	v_mul_f32_e32 v10, 0x39800000, v10
	v_cos_f32_e32 v11, v10
	v_sin_f32_e32 v10, v10
	s_nop 0
	v_pk_mul_f32 v[10:11], v[10:11], s[54:55] op_sel_hi:[1,0]
	s_nop 0
	v_pk_mul_f32 v[12:13], v[10:11], v[14:15]
	v_pk_mul_f32 v[10:11], v[10:11], v[30:31]
	v_sub_f32_e32 v14, v13, v12
	v_add_f32_e32 v10, v10, v11
	v_xor_b32_e32 v15, 0x80000000, v10
	v_add3_u32 v10, v114, v35, s12
	v_and_b32_e32 v10, 0xffe, v10
	v_cvt_f32_u32_e32 v10, v10
	v_mov_b32_e32 v12, v32
	v_mov_b32_e32 v13, v16
	s_movk_i32 s12, 0x760
	v_mul_f32_e32 v10, 0x39800000, v10
	v_cos_f32_e32 v11, v10
	v_sin_f32_e32 v10, v10
	s_nop 0
	v_pk_mul_f32 v[10:11], v[10:11], s[54:55] op_sel_hi:[1,0]
	s_nop 0
	v_pk_mul_f32 v[12:13], v[10:11], v[12:13]
	s_nop 0
	v_sub_f32_e32 v30, v13, v12
	v_mov_b32_e32 v12, v16
	v_mov_b32_e32 v13, v32
	v_pk_mul_f32 v[10:11], v[10:11], v[12:13]
	v_mov_b32_e32 v16, v33
	v_add_f32_e32 v10, v10, v11
	v_xor_b32_e32 v31, 0x80000000, v10
	v_add3_u32 v10, v114, v34, s12
	v_and_b32_e32 v10, 0xfff, v10
	v_cvt_f32_u32_e32 v10, v10
	v_mov_b32_e32 v32, v17
	v_cvt_pk_bf16_f32 v114, v9, v40
	v_cvt_pk_bf16_f32 v115, v27, v24
	v_mul_f32_e32 v10, 0x39800000, v10
	v_cos_f32_e32 v11, v10
	v_sin_f32_e32 v10, v10
	v_cvt_pk_bf16_f32 v116, v28, v14
	v_readlane_b32 s12, v245, 43
	v_pk_mul_f32 v[10:11], v[10:11], s[54:55] op_sel_hi:[1,0]
	s_nop 0
	v_pk_mul_f32 v[12:13], v[10:11], v[16:17]
	v_pk_mul_f32 v[10:11], v[10:11], v[32:33]
	v_sub_f32_e32 v12, v13, v12
	v_add_f32_e32 v10, v10, v11
	v_xor_b32_e32 v10, 0x80000000, v10
	v_cvt_pk_bf16_f32 v117, v30, v12
	v_cvt_pk_bf16_f32 v118, v45, v26
	v_cvt_pk_bf16_f32 v119, v39, v25
	v_cvt_pk_bf16_f32 v120, v29, v15
	v_cvt_pk_bf16_f32 v121, v31, v10
	v_lshl_add_u32 v10, v0, 3, v133
	v_lshlrev_b32_e32 v13, 4, v132
	v_add_u32_e32 v11, s4, v10
	v_xor_b32_e32 v14, 16, v13
	v_add_u32_e32 v2, v11, v13
	v_add_u32_e32 v4, v11, v14
	ds_read_b64 v[2:3], v2
	ds_read_b64 v[4:5], v4
	v_add_u32_e32 v12, s5, v10
	v_add_u32_e32 v6, v12, v13
	v_add_u32_e32 v8, v12, v14
	ds_read_b64 v[6:7], v6
	ds_read_b64 v[8:9], v8
	s_waitcnt lgkmcnt(0)
	v_mfma_f32_32x32x16_bf16 v[50:65], v[2:5], v[106:109], 0
	v_xor_b32_e32 v136, 32, v13
	v_xor_b32_e32 v137, 48, v13
	v_xor_b32_e32 v138, 64, v13
	v_xor_b32_e32 v139, 0x50, v13
	v_xor_b32_e32 v140, 0x60, v13
	v_xor_b32_e32 v141, 0x70, v13
	v_add_u32_e32 v142, 0x1000, v10
	v_mfma_f32_32x32x16_bf16 v[34:49], v[2:5], v[74:77], 0
	v_add_u32_e32 v2, v11, v136
	v_add_u32_e32 v4, v11, v137
	ds_read_b64 v[2:3], v2
	ds_read_b64 v[4:5], v4
	v_mfma_f32_32x32x16_bf16 v[50:65], v[6:9], v[110:113], v[50:65]
	v_mfma_f32_32x32x16_bf16 v[34:49], v[6:9], v[78:81], v[34:49]
	v_add_u32_e32 v6, v12, v136
	v_add_u32_e32 v8, v12, v137
	ds_read_b64 v[6:7], v6
	ds_read_b64 v[8:9], v8
	s_waitcnt lgkmcnt(0)
	v_mfma_f32_32x32x16_bf16 v[50:65], v[2:5], v[98:101], v[50:65]
	v_mfma_f32_32x32x16_bf16 v[34:49], v[2:5], v[66:69], v[34:49]
	v_add_u32_e32 v2, v11, v138
	v_add_u32_e32 v4, v11, v139
	ds_read_b64 v[2:3], v2
	ds_read_b64 v[4:5], v4
	v_mfma_f32_32x32x16_bf16 v[50:65], v[6:9], v[102:105], v[50:65]
	v_mfma_f32_32x32x16_bf16 v[34:49], v[6:9], v[70:73], v[34:49]
	v_add_u32_e32 v6, v12, v138
	v_add_u32_e32 v8, v12, v139
	ds_read_b64 v[6:7], v6
	ds_read_b64 v[8:9], v8
	s_waitcnt lgkmcnt(0)
	v_mfma_f32_32x32x16_bf16 v[50:65], v[2:5], v[90:93], v[50:65]
	v_mfma_f32_32x32x16_bf16 v[34:49], v[2:5], v[122:125], v[34:49]
	v_add_u32_e32 v2, v11, v140
	v_add_u32_e32 v4, v11, v141
	ds_read_b64 v[2:3], v2
	ds_read_b64 v[4:5], v4
	v_mfma_f32_32x32x16_bf16 v[50:65], v[6:9], v[94:97], v[50:65]
	v_mfma_f32_32x32x16_bf16 v[34:49], v[6:9], v[126:129], v[34:49]
	v_add_u32_e32 v6, v12, v140
	v_add_u32_e32 v8, v12, v141
	ds_read_b64 v[6:7], v6
	ds_read_b64 v[8:9], v8
	s_waitcnt lgkmcnt(0)
	v_mfma_f32_32x32x16_bf16 v[50:65], v[2:5], v[82:85], v[50:65]
	v_mfma_f32_32x32x16_bf16 v[34:49], v[2:5], v[114:117], v[34:49]
	v_add3_u32 v2, s4, v13, v142
	v_add3_u32 v4, s4, v14, v142
	ds_read_b64 v[2:3], v2
	ds_read_b64 v[4:5], v4
	v_mfma_f32_32x32x16_bf16 v[50:65], v[6:9], v[86:89], v[50:65]
	v_mfma_f32_32x32x16_bf16 v[34:49], v[6:9], v[118:121], v[34:49]
	v_add3_u32 v6, s5, v13, v142
	ds_read_b64 v[132:133], v6
	v_add3_u32 v6, s5, v14, v142
	ds_read_b64 v[134:135], v6
	s_waitcnt lgkmcnt(0)
	v_mfma_f32_32x32x16_bf16 v[18:33], v[2:5], v[106:109], 0
	v_mfma_f32_32x32x16_bf16 v[2:17], v[2:5], v[74:77], 0
	v_add3_u32 v74, s4, v136, v142
	v_add3_u32 v76, s4, v137, v142
	ds_read_b64 v[74:75], v74
	ds_read_b64 v[76:77], v76
	v_mfma_f32_32x32x16_bf16 v[18:33], v[132:135], v[110:113], v[18:33]
	v_mfma_f32_32x32x16_bf16 v[2:17], v[132:135], v[78:81], v[2:17]
	v_add3_u32 v78, s5, v136, v142
	v_add3_u32 v80, s5, v137, v142
	ds_read_b64 v[78:79], v78
	ds_read_b64 v[80:81], v80
	s_waitcnt lgkmcnt(0)
	v_mfma_f32_32x32x16_bf16 v[18:33], v[74:77], v[98:101], v[18:33]
	v_mfma_f32_32x32x16_bf16 v[2:17], v[74:77], v[66:69], v[2:17]
	v_add3_u32 v66, s4, v138, v142
	v_add3_u32 v68, s4, v139, v142
	ds_read_b64 v[66:67], v66
	ds_read_b64 v[68:69], v68
	v_mfma_f32_32x32x16_bf16 v[18:33], v[78:81], v[102:105], v[18:33]
	v_mfma_f32_32x32x16_bf16 v[2:17], v[78:81], v[70:73], v[2:17]
	v_add3_u32 v70, s5, v138, v142
	v_add3_u32 v72, s5, v139, v142
	ds_read_b64 v[70:71], v70
	ds_read_b64 v[72:73], v72
	s_waitcnt lgkmcnt(0)
	v_mfma_f32_32x32x16_bf16 v[18:33], v[66:69], v[90:93], v[18:33]
	v_mfma_f32_32x32x16_bf16 v[2:17], v[66:69], v[122:125], v[2:17]
	v_add3_u32 v66, s4, v140, v142
	v_add3_u32 v68, s4, v141, v142
	ds_read_b64 v[66:67], v66
	ds_read_b64 v[68:69], v68
	v_readlane_b32 s4, v245, 42
	v_mfma_f32_32x32x16_bf16 v[18:33], v[70:73], v[94:97], v[18:33]
	v_mfma_f32_32x32x16_bf16 v[2:17], v[70:73], v[126:129], v[2:17]
	v_add3_u32 v70, s5, v140, v142
	v_add3_u32 v72, s5, v141, v142
	ds_read_b64 v[70:71], v70
	ds_read_b64 v[72:73], v72
	s_waitcnt vmcnt(0) lgkmcnt(0)
	s_barrier
	v_mfma_f32_32x32x16_bf16 v[18:33], v[66:69], v[82:85], v[18:33]
	v_mfma_f32_32x32x16_bf16 v[2:17], v[66:69], v[114:117], v[2:17]
	v_bfe_u32 v66, v50, 16, 1
	v_add3_u32 v50, v50, v66, s49
	v_lshrrev_b32_e32 v66, 16, v50
	v_lshlrev_b32_e32 v50, 4, v131
	v_lshl_or_b32 v50, v0, 12, v50
	v_add_u32_e32 v0, s4, v50
	s_mov_b64 s[4:5], -1
	v_mfma_f32_32x32x16_bf16 v[18:33], v[70:73], v[86:89], v[18:33]
	v_add_u32_e32 v50, s12, v50
	v_bfe_u32 v67, v51, 16, 1
	ds_write_b16 v0, v66
	v_mfma_f32_32x32x16_bf16 v[2:17], v[70:73], v[118:121], v[2:17]
	s_cbranch_vccz .LBB0_355
	ds_write_b16 v50, v66
	v_add3_u32 v66, v51, v67, s49
	v_lshrrev_b32_e32 v66, 16, v66
	s_mov_b64 s[4:5], 0
	ds_write_b16 v0, v66 offset:1024
	ds_write_b16 v50, v66 offset:1024
